# P0a adaLN GEMV: all 32 weight loads of a thread issued up front (before the silu fill), k loop unrolled
# baseline (speedup 1.0000x reference)
.LBB0_9:
	s_mov_b64 s[50:51], 0x3000
	v_mov_b32_e32 v116, v8
	v_ashrrev_i32_e32 v117, 31, v8
	s_nop 0
	v_lshl_add_u64 v[116:117], v[116:117], 2, v[6:7]
	global_load_dword v160, v[116:117], off
	v_lshl_add_u64 v[116:117], v[116:117], 0, s[50:51]
	global_load_dword v162, v[116:117], off
	v_lshl_add_u64 v[116:117], v[116:117], 0, s[50:51]
	global_load_dword v164, v[116:117], off
	v_lshl_add_u64 v[116:117], v[116:117], 0, s[50:51]
	global_load_dword v166, v[116:117], off
	v_lshl_add_u64 v[116:117], v[116:117], 0, s[50:51]
	global_load_dword v168, v[116:117], off
	v_lshl_add_u64 v[116:117], v[116:117], 0, s[50:51]
	global_load_dword v170, v[116:117], off
	v_lshl_add_u64 v[116:117], v[116:117], 0, s[50:51]
	global_load_dword v172, v[116:117], off
	v_lshl_add_u64 v[116:117], v[116:117], 0, s[50:51]
	global_load_dword v174, v[116:117], off
	v_lshl_add_u64 v[116:117], v[116:117], 0, s[50:51]
	global_load_dword v176, v[116:117], off
	v_lshl_add_u64 v[116:117], v[116:117], 0, s[50:51]
	global_load_dword v178, v[116:117], off
	v_lshl_add_u64 v[116:117], v[116:117], 0, s[50:51]
	global_load_dword v180, v[116:117], off
	v_lshl_add_u64 v[116:117], v[116:117], 0, s[50:51]
	global_load_dword v182, v[116:117], off
	v_lshl_add_u64 v[116:117], v[116:117], 0, s[50:51]
	global_load_dword v184, v[116:117], off
	v_lshl_add_u64 v[116:117], v[116:117], 0, s[50:51]
	global_load_dword v186, v[116:117], off
	v_lshl_add_u64 v[116:117], v[116:117], 0, s[50:51]
	global_load_dword v188, v[116:117], off
	v_lshl_add_u64 v[116:117], v[116:117], 0, s[50:51]
	global_load_dword v190, v[116:117], off
	v_lshl_add_u64 v[116:117], v[116:117], 0, s[50:51]
	global_load_dword v192, v[116:117], off
	v_lshl_add_u64 v[116:117], v[116:117], 0, s[50:51]
	global_load_dword v194, v[116:117], off
	v_lshl_add_u64 v[116:117], v[116:117], 0, s[50:51]
	global_load_dword v196, v[116:117], off
	v_lshl_add_u64 v[116:117], v[116:117], 0, s[50:51]
	global_load_dword v200, v[116:117], off
	v_lshl_add_u64 v[116:117], v[116:117], 0, s[50:51]
	global_load_dword v202, v[116:117], off
	v_lshl_add_u64 v[116:117], v[116:117], 0, s[50:51]
	global_load_dword v204, v[116:117], off
	v_lshl_add_u64 v[116:117], v[116:117], 0, s[50:51]
	global_load_dword v206, v[116:117], off
	v_lshl_add_u64 v[116:117], v[116:117], 0, s[50:51]
	global_load_dword v208, v[116:117], off
	v_lshl_add_u64 v[116:117], v[116:117], 0, s[50:51]
	global_load_dword v210, v[116:117], off
	v_lshl_add_u64 v[116:117], v[116:117], 0, s[50:51]
	global_load_dword v212, v[116:117], off
	v_lshl_add_u64 v[116:117], v[116:117], 0, s[50:51]
	global_load_dword v214, v[116:117], off
	v_lshl_add_u64 v[116:117], v[116:117], 0, s[50:51]
	global_load_dword v216, v[116:117], off
	v_lshl_add_u64 v[116:117], v[116:117], 0, s[50:51]
	global_load_dword v218, v[116:117], off
	v_lshl_add_u64 v[116:117], v[116:117], 0, s[50:51]
	global_load_dword v220, v[116:117], off
	v_lshl_add_u64 v[116:117], v[116:117], 0, s[50:51]
	global_load_dword v222, v[116:117], off
	v_lshl_add_u64 v[116:117], v[116:117], 0, s[50:51]
	global_load_dword v224, v[116:117], off
	s_and_saveexec_b64 s[14:15], vcc
	s_cbranch_execz .LBB0_16
	s_load_dwordx2 s[28:29], s[0:1], 0x8
	s_load_dwordx2 s[16:17], s[0:1], 0x18
	v_add_u32_e32 v155, 0x10000, v5
	s_waitcnt lgkmcnt(0)
	global_load_dword v120, v5, s[28:29]
	global_load_dword v121, v5, s[28:29] offset:2048
	s_add_u32 s28, s28, 0x1000
	s_addc_u32 s29, s29, 0
	global_load_dword v122, v5, s[28:29]
	global_load_dword v123, v5, s[28:29] offset:2048
	s_add_u32 s28, s28, 0x1000
	s_addc_u32 s29, s29, 0
	global_load_dword v124, v5, s[28:29]
	global_load_dword v125, v5, s[28:29] offset:2048
	s_add_u32 s28, s28, 0x1000
	s_addc_u32 s29, s29, 0
	global_load_dword v126, v5, s[28:29]
	global_load_dword v127, v5, s[28:29] offset:2048
	s_add_u32 s28, s28, 0x1000
	s_addc_u32 s29, s29, 0
	global_load_dword v128, v5, s[28:29]
	global_load_dword v129, v5, s[28:29] offset:2048
	s_add_u32 s28, s28, 0x1000
	s_addc_u32 s29, s29, 0
	global_load_dword v130, v5, s[28:29]
	global_load_dword v131, v5, s[28:29] offset:2048
	s_add_u32 s28, s28, 0x1000
	s_addc_u32 s29, s29, 0
	global_load_dword v132, v5, s[28:29]
	global_load_dword v133, v5, s[28:29] offset:2048
	s_add_u32 s28, s28, 0x1000
	s_addc_u32 s29, s29, 0
	global_load_dword v134, v5, s[28:29]
	global_load_dword v135, v5, s[28:29] offset:2048
	s_add_u32 s28, s28, 0x1000
	s_addc_u32 s29, s29, 0
	global_load_dword v136, v5, s[28:29]
	global_load_dword v137, v5, s[28:29] offset:2048
	s_add_u32 s28, s28, 0x1000
	s_addc_u32 s29, s29, 0
	global_load_dword v138, v5, s[28:29]
	global_load_dword v139, v5, s[28:29] offset:2048
	s_add_u32 s28, s28, 0x1000
	s_addc_u32 s29, s29, 0
	global_load_dword v140, v5, s[28:29]
	global_load_dword v141, v5, s[28:29] offset:2048
	s_add_u32 s28, s28, 0x1000
	s_addc_u32 s29, s29, 0
	global_load_dword v142, v5, s[28:29]
	global_load_dword v143, v5, s[28:29] offset:2048
	s_add_u32 s28, s28, 0x1000
	s_addc_u32 s29, s29, 0
	global_load_dword v144, v5, s[28:29]
	global_load_dword v145, v5, s[28:29] offset:2048
	s_add_u32 s28, s28, 0x1000
	s_addc_u32 s29, s29, 0
	global_load_dword v146, v5, s[28:29]
	global_load_dword v147, v5, s[28:29] offset:2048
	s_add_u32 s28, s28, 0x1000
	s_addc_u32 s29, s29, 0
	global_load_dword v148, v5, s[28:29]
	global_load_dword v149, v5, s[28:29] offset:2048
	s_add_u32 s28, s28, 0x1000
	s_addc_u32 s29, s29, 0
	global_load_dword v150, v5, s[28:29]
	global_load_dword v151, v5, s[28:29] offset:2048
	global_load_dword v152, v5, s[16:17]
	global_load_dword v153, v5, s[16:17] offset:2048
	s_waitcnt vmcnt(32)
	v_mul_f32_e32 v156, 0xbfb8aa3b, v120
	v_mul_f32_e32 v157, 0xbfb8aa3b, v121
	v_exp_f32_e32 v156, v156
	v_exp_f32_e32 v157, v157
	v_add_f32_e32 v156, 1.0, v156
	v_add_f32_e32 v157, 1.0, v157
	v_rcp_f32_e32 v156, v156
	v_rcp_f32_e32 v157, v157
	v_mul_f32_e32 v120, v120, v156
	v_mul_f32_e32 v121, v121, v157
	ds_write_b32 v5, v120
	ds_write_b32 v5, v121 offset:2048
	s_waitcnt vmcnt(30)
	v_mul_f32_e32 v156, 0xbfb8aa3b, v122
	v_mul_f32_e32 v157, 0xbfb8aa3b, v123
	v_exp_f32_e32 v156, v156
	v_exp_f32_e32 v157, v157
	v_add_f32_e32 v156, 1.0, v156
	v_add_f32_e32 v157, 1.0, v157
	v_rcp_f32_e32 v156, v156
	v_rcp_f32_e32 v157, v157
	v_mul_f32_e32 v122, v122, v156
	v_mul_f32_e32 v123, v123, v157
	ds_write_b32 v5, v122 offset:4096
	ds_write_b32 v5, v123 offset:6144
	s_waitcnt vmcnt(28)
	v_mul_f32_e32 v156, 0xbfb8aa3b, v124
	v_mul_f32_e32 v157, 0xbfb8aa3b, v125
	v_exp_f32_e32 v156, v156
	v_exp_f32_e32 v157, v157
	v_add_f32_e32 v156, 1.0, v156
	v_add_f32_e32 v157, 1.0, v157
	v_rcp_f32_e32 v156, v156
	v_rcp_f32_e32 v157, v157
	v_mul_f32_e32 v124, v124, v156
	v_mul_f32_e32 v125, v125, v157
	ds_write_b32 v5, v124 offset:8192
	ds_write_b32 v5, v125 offset:10240
	s_waitcnt vmcnt(26)
	v_mul_f32_e32 v156, 0xbfb8aa3b, v126
	v_mul_f32_e32 v157, 0xbfb8aa3b, v127
	v_exp_f32_e32 v156, v156
	v_exp_f32_e32 v157, v157
	v_add_f32_e32 v156, 1.0, v156
	v_add_f32_e32 v157, 1.0, v157
	v_rcp_f32_e32 v156, v156
	v_rcp_f32_e32 v157, v157
	v_mul_f32_e32 v126, v126, v156
	v_mul_f32_e32 v127, v127, v157
	ds_write_b32 v5, v126 offset:12288
	ds_write_b32 v5, v127 offset:14336
	s_waitcnt vmcnt(24)
	v_mul_f32_e32 v156, 0xbfb8aa3b, v128
	v_mul_f32_e32 v157, 0xbfb8aa3b, v129
	v_exp_f32_e32 v156, v156
	v_exp_f32_e32 v157, v157
	v_add_f32_e32 v156, 1.0, v156
	v_add_f32_e32 v157, 1.0, v157
	v_rcp_f32_e32 v156, v156
	v_rcp_f32_e32 v157, v157
	v_mul_f32_e32 v128, v128, v156
	v_mul_f32_e32 v129, v129, v157
	ds_write_b32 v5, v128 offset:16384
	ds_write_b32 v5, v129 offset:18432
	s_waitcnt vmcnt(22)
	v_mul_f32_e32 v156, 0xbfb8aa3b, v130
	v_mul_f32_e32 v157, 0xbfb8aa3b, v131
	v_exp_f32_e32 v156, v156
	v_exp_f32_e32 v157, v157
	v_add_f32_e32 v156, 1.0, v156
	v_add_f32_e32 v157, 1.0, v157
	v_rcp_f32_e32 v156, v156
	v_rcp_f32_e32 v157, v157
	v_mul_f32_e32 v130, v130, v156
	v_mul_f32_e32 v131, v131, v157
	ds_write_b32 v5, v130 offset:20480
	ds_write_b32 v5, v131 offset:22528
	s_waitcnt vmcnt(20)
	v_mul_f32_e32 v156, 0xbfb8aa3b, v132
	v_mul_f32_e32 v157, 0xbfb8aa3b, v133
	v_exp_f32_e32 v156, v156
	v_exp_f32_e32 v157, v157
	v_add_f32_e32 v156, 1.0, v156
	v_add_f32_e32 v157, 1.0, v157
	v_rcp_f32_e32 v156, v156
	v_rcp_f32_e32 v157, v157
	v_mul_f32_e32 v132, v132, v156
	v_mul_f32_e32 v133, v133, v157
	ds_write_b32 v5, v132 offset:24576
	ds_write_b32 v5, v133 offset:26624
	s_waitcnt vmcnt(18)
	v_mul_f32_e32 v156, 0xbfb8aa3b, v134
	v_mul_f32_e32 v157, 0xbfb8aa3b, v135
	v_exp_f32_e32 v156, v156
	v_exp_f32_e32 v157, v157
	v_add_f32_e32 v156, 1.0, v156
	v_add_f32_e32 v157, 1.0, v157
	v_rcp_f32_e32 v156, v156
	v_rcp_f32_e32 v157, v157
	v_mul_f32_e32 v134, v134, v156
	v_mul_f32_e32 v135, v135, v157
	ds_write_b32 v5, v134 offset:28672
	ds_write_b32 v5, v135 offset:30720
	s_waitcnt vmcnt(16)
	v_mul_f32_e32 v156, 0xbfb8aa3b, v136
	v_mul_f32_e32 v157, 0xbfb8aa3b, v137
	v_exp_f32_e32 v156, v156
	v_exp_f32_e32 v157, v157
	v_add_f32_e32 v156, 1.0, v156
	v_add_f32_e32 v157, 1.0, v157
	v_rcp_f32_e32 v156, v156
	v_rcp_f32_e32 v157, v157
	v_mul_f32_e32 v136, v136, v156
	v_mul_f32_e32 v137, v137, v157
	ds_write_b32 v5, v136 offset:32768
	ds_write_b32 v5, v137 offset:34816
	s_waitcnt vmcnt(14)
	v_mul_f32_e32 v156, 0xbfb8aa3b, v138
	v_mul_f32_e32 v157, 0xbfb8aa3b, v139
	v_exp_f32_e32 v156, v156
	v_exp_f32_e32 v157, v157
	v_add_f32_e32 v156, 1.0, v156
	v_add_f32_e32 v157, 1.0, v157
	v_rcp_f32_e32 v156, v156
	v_rcp_f32_e32 v157, v157
	v_mul_f32_e32 v138, v138, v156
	v_mul_f32_e32 v139, v139, v157
	ds_write_b32 v5, v138 offset:36864
	ds_write_b32 v5, v139 offset:38912
	s_waitcnt vmcnt(12)
	v_mul_f32_e32 v156, 0xbfb8aa3b, v140
	v_mul_f32_e32 v157, 0xbfb8aa3b, v141
	v_exp_f32_e32 v156, v156
	v_exp_f32_e32 v157, v157
	v_add_f32_e32 v156, 1.0, v156
	v_add_f32_e32 v157, 1.0, v157
	v_rcp_f32_e32 v156, v156
	v_rcp_f32_e32 v157, v157
	v_mul_f32_e32 v140, v140, v156
	v_mul_f32_e32 v141, v141, v157
	ds_write_b32 v5, v140 offset:40960
	ds_write_b32 v5, v141 offset:43008
	s_waitcnt vmcnt(10)
	v_mul_f32_e32 v156, 0xbfb8aa3b, v142
	v_mul_f32_e32 v157, 0xbfb8aa3b, v143
	v_exp_f32_e32 v156, v156
	v_exp_f32_e32 v157, v157
	v_add_f32_e32 v156, 1.0, v156
	v_add_f32_e32 v157, 1.0, v157
	v_rcp_f32_e32 v156, v156
	v_rcp_f32_e32 v157, v157
	v_mul_f32_e32 v142, v142, v156
	v_mul_f32_e32 v143, v143, v157
	ds_write_b32 v5, v142 offset:45056
	ds_write_b32 v5, v143 offset:47104
	s_waitcnt vmcnt(8)
	v_mul_f32_e32 v156, 0xbfb8aa3b, v144
	v_mul_f32_e32 v157, 0xbfb8aa3b, v145
	v_exp_f32_e32 v156, v156
	v_exp_f32_e32 v157, v157
	v_add_f32_e32 v156, 1.0, v156
	v_add_f32_e32 v157, 1.0, v157
	v_rcp_f32_e32 v156, v156
	v_rcp_f32_e32 v157, v157
	v_mul_f32_e32 v144, v144, v156
	v_mul_f32_e32 v145, v145, v157
	ds_write_b32 v5, v144 offset:49152
	ds_write_b32 v5, v145 offset:51200
	s_waitcnt vmcnt(6)
	v_mul_f32_e32 v156, 0xbfb8aa3b, v146
	v_mul_f32_e32 v157, 0xbfb8aa3b, v147
	v_exp_f32_e32 v156, v156
	v_exp_f32_e32 v157, v157
	v_add_f32_e32 v156, 1.0, v156
	v_add_f32_e32 v157, 1.0, v157
	v_rcp_f32_e32 v156, v156
	v_rcp_f32_e32 v157, v157
	v_mul_f32_e32 v146, v146, v156
	v_mul_f32_e32 v147, v147, v157
	ds_write_b32 v5, v146 offset:53248
	ds_write_b32 v5, v147 offset:55296
	s_waitcnt vmcnt(4)
	v_mul_f32_e32 v156, 0xbfb8aa3b, v148
	v_mul_f32_e32 v157, 0xbfb8aa3b, v149
	v_exp_f32_e32 v156, v156
	v_exp_f32_e32 v157, v157
	v_add_f32_e32 v156, 1.0, v156
	v_add_f32_e32 v157, 1.0, v157
	v_rcp_f32_e32 v156, v156
	v_rcp_f32_e32 v157, v157
	v_mul_f32_e32 v148, v148, v156
	v_mul_f32_e32 v149, v149, v157
	ds_write_b32 v5, v148 offset:57344
	ds_write_b32 v5, v149 offset:59392
	s_waitcnt vmcnt(2)
	v_mul_f32_e32 v156, 0xbfb8aa3b, v150
	v_mul_f32_e32 v157, 0xbfb8aa3b, v151
	v_exp_f32_e32 v156, v156
	v_exp_f32_e32 v157, v157
	v_add_f32_e32 v156, 1.0, v156
	v_add_f32_e32 v157, 1.0, v157
	v_rcp_f32_e32 v156, v156
	v_rcp_f32_e32 v157, v157
	v_mul_f32_e32 v150, v150, v156
	v_mul_f32_e32 v151, v151, v157
	ds_write_b32 v5, v150 offset:61440
	ds_write_b32 v5, v151 offset:63488
	s_waitcnt vmcnt(0)
	v_mul_f32_e32 v156, 0xbfb8aa3b, v152
	v_mul_f32_e32 v157, 0xbfb8aa3b, v153
	v_exp_f32_e32 v156, v156
	v_exp_f32_e32 v157, v157
	v_add_f32_e32 v156, 1.0, v156
	v_add_f32_e32 v157, 1.0, v157
	v_rcp_f32_e32 v156, v156
	v_rcp_f32_e32 v157, v157
	v_mul_f32_e32 v152, v152, v156
	v_mul_f32_e32 v153, v153, v157
	ds_write_b32 v155, v152
	ds_write_b32 v155, v153 offset:2048
.LBB0_16:
	s_or_b64 exec, exec, s[14:15]
	v_ashrrev_i32_e32 v9, 31, v8
	v_mov_b32_e32 v14, 0
	v_lshl_add_u64 v[12:13], v[8:9], 2, v[6:7]
	s_mov_b64 s[14:15], 0
	v_mov_b32_e32 v9, v38
	v_mov_b32_e32 v40, v37
	v_mov_b32_e32 v15, v14
	v_mov_b32_e32 v16, v14
	v_mov_b32_e32 v17, v14
	v_mov_b32_e32 v18, v14
	v_mov_b32_e32 v19, v14
	v_mov_b32_e32 v20, v14
	v_mov_b32_e32 v21, v14
	v_mov_b32_e32 v22, v14
	v_mov_b32_e32 v23, v14
	v_mov_b32_e32 v24, v14
	v_mov_b32_e32 v25, v14
	v_mov_b32_e32 v26, v14
	v_mov_b32_e32 v27, v14
	v_mov_b32_e32 v28, v14
	v_mov_b32_e32 v29, v14
	v_mov_b32_e32 v41, v14
	s_waitcnt lgkmcnt(0)
	s_barrier
	s_waitcnt vmcnt(0)
	v_add_u32_e32 v48, 0x1000, v9
	v_add_u32_e32 v50, 0x2000, v9
	v_add_u32_e32 v52, 0x3000, v9
	v_add_u32_e32 v54, 0x4000, v9
	v_add_u32_e32 v56, 0x5000, v9
	v_add_u32_e32 v58, 0x6000, v9
	v_add_u32_e32 v60, 0x7000, v9
	v_add_u32_e32 v62, 0x8000, v9
	v_add_u32_e32 v64, 0x9000, v9
	v_add_u32_e32 v66, 0xa000, v9
	v_add_u32_e32 v68, 0xb000, v9
	v_add_u32_e32 v70, 0xc000, v9
	ds_read2_b32 v[30:31], v9 offset1:1
	ds_read2_b32 v[32:33], v9 offset0:2 offset1:3
	v_add_u32_e32 v72, 0xd000, v9
	v_add_u32_e32 v74, 0xe000, v9
	v_add_u32_e32 v76, 0xf000, v9
	v_add_u32_e32 v78, 0x10000, v9
	ds_read2_b32 v[48:49], v48 offset1:1
	ds_read2_b32 v[50:51], v50 offset1:1
	ds_read2_b32 v[52:53], v52 offset1:1
	ds_read2_b32 v[54:55], v54 offset1:1
	ds_read2_b32 v[56:57], v56 offset1:1
	ds_read2_b32 v[58:59], v58 offset1:1
	ds_read2_b32 v[60:61], v60 offset1:1
	ds_read2_b32 v[62:63], v62 offset1:1
	ds_read2_b32 v[64:65], v64 offset1:1
	ds_read2_b32 v[66:67], v66 offset1:1
	ds_read2_b32 v[68:69], v68 offset1:1
	ds_read2_b32 v[70:71], v70 offset1:1
	v_add_u32_e32 v80, 0x1008, v9
	v_add_u32_e32 v82, 0x2008, v9
	v_add_u32_e32 v84, 0x3008, v9
	v_add_u32_e32 v86, 0x4008, v9
	v_add_u32_e32 v88, 0x5008, v9
	v_add_u32_e32 v90, 0x6008, v9
	v_add_u32_e32 v92, 0x7008, v9
	v_add_u32_e32 v94, 0x8008, v9
	v_add_u32_e32 v96, 0x9008, v9
	v_add_u32_e32 v98, 0xa008, v9
	v_add_u32_e32 v100, 0xb008, v9
	v_add_u32_e32 v102, 0xc008, v9
	ds_read2_b32 v[72:73], v72 offset1:1
	ds_read2_b32 v[74:75], v74 offset1:1
	ds_read2_b32 v[76:77], v76 offset1:1
	ds_read2_b32 v[78:79], v78 offset1:1
	ds_read2_b32 v[80:81], v80 offset1:1
	ds_read2_b32 v[82:83], v82 offset1:1
	ds_read2_b32 v[84:85], v84 offset1:1
	ds_read2_b32 v[86:87], v86 offset1:1
	ds_read2_b32 v[88:89], v88 offset1:1
	ds_read2_b32 v[90:91], v90 offset1:1
	ds_read2_b32 v[92:93], v92 offset1:1
	ds_read2_b32 v[94:95], v94 offset1:1
	ds_read2_b32 v[96:97], v96 offset1:1
	ds_read2_b32 v[98:99], v98 offset1:1
	ds_read2_b32 v[100:101], v100 offset1:1
	ds_read2_b32 v[102:103], v102 offset1:1
	v_add_u32_e32 v104, 0xd008, v9
	v_add_u32_e32 v106, 0xe008, v9
	v_add_u32_e32 v108, 0xf008, v9
	v_add_u32_e32 v110, 0x10008, v9
	ds_read2_b32 v[104:105], v104 offset1:1
	ds_read2_b32 v[106:107], v106 offset1:1
	ds_read2_b32 v[108:109], v108 offset1:1
	ds_read2_b32 v[110:111], v110 offset1:1
	s_waitcnt lgkmcnt(14)
	v_mov_b32_e32 v112, v30
	v_mov_b32_e32 v113, v48
	v_mov_b32_e32 v114, v50
	v_mov_b32_e32 v115, v52
	v_mov_b32_e32 v52, v51
	v_mov_b32_e32 v50, v54
	v_mov_b32_e32 v51, v56
	v_mov_b32_e32 v56, v55
	v_mov_b32_e32 v54, v58
	v_mov_b32_e32 v55, v60
	v_mov_b32_e32 v60, v59
	v_mov_b32_e32 v58, v62
	v_mov_b32_e32 v59, v64
	v_mov_b32_e32 v64, v63
	v_mov_b32_e32 v62, v66
	v_mov_b32_e32 v63, v68
	v_mov_b32_e32 v68, v67
	v_mov_b32_e32 v66, v70
	v_mov_b32_e32 v67, v72
	v_mov_b32_e32 v72, v71
	v_mov_b32_e32 v70, v74
	v_mov_b32_e32 v71, v76
	v_mov_b32_e32 v48, v31
	v_mov_b32_e32 v76, v75
	v_mov_b32_e32 v30, v32
	v_mov_b32_e32 v31, v80
	v_mov_b32_e32 v80, v33
	v_mov_b32_e32 v32, v82
	s_waitcnt lgkmcnt(13)
	v_mov_b32_e32 v33, v84
	v_mov_b32_e32 v84, v83
	s_waitcnt lgkmcnt(12)
	v_mov_b32_e32 v74, v86
	s_waitcnt lgkmcnt(11)
	v_mov_b32_e32 v75, v88
	v_mov_b32_e32 v88, v87
	s_waitcnt lgkmcnt(10)
	v_mov_b32_e32 v82, v90
	s_waitcnt lgkmcnt(9)
	v_mov_b32_e32 v83, v92
	v_mov_b32_e32 v92, v91
	s_waitcnt lgkmcnt(8)
	v_mov_b32_e32 v86, v94
	s_waitcnt lgkmcnt(7)
	v_mov_b32_e32 v87, v96
	v_mov_b32_e32 v96, v95
	s_waitcnt lgkmcnt(6)
	v_mov_b32_e32 v90, v98
	s_waitcnt lgkmcnt(5)
	v_mov_b32_e32 v91, v100
	v_mov_b32_e32 v100, v99
	s_waitcnt lgkmcnt(4)
	v_mov_b32_e32 v94, v102
	s_waitcnt lgkmcnt(3)
	v_mov_b32_e32 v95, v104
	s_waitcnt lgkmcnt(2)
	v_mov_b32_e32 v98, v106
	v_pk_fma_f32 v[14:15], v[160:161], v[112:113], v[14:15] op_sel_hi:[0,1,1]
	v_pk_fma_f32 v[16:17], v[160:161], v[114:115], v[16:17] op_sel_hi:[0,1,1]
	v_pk_fma_f32 v[18:19], v[160:161], v[50:51], v[18:19] op_sel_hi:[0,1,1]
	v_pk_fma_f32 v[20:21], v[160:161], v[54:55], v[20:21] op_sel_hi:[0,1,1]
	v_pk_fma_f32 v[22:23], v[160:161], v[58:59], v[22:23] op_sel_hi:[0,1,1]
	v_pk_fma_f32 v[24:25], v[160:161], v[62:63], v[24:25] op_sel_hi:[0,1,1]
	v_pk_fma_f32 v[26:27], v[160:161], v[66:67], v[26:27] op_sel_hi:[0,1,1]
	v_pk_fma_f32 v[28:29], v[160:161], v[70:71], v[28:29] op_sel_hi:[0,1,1]
	v_fmac_f32_e32 v41, v160, v78
	s_waitcnt lgkmcnt(1)
	v_mov_b32_e32 v99, v108
	v_pk_fma_f32 v[14:15], v[162:163], v[48:49], v[14:15] op_sel_hi:[0,1,1]
	v_pk_fma_f32 v[16:17], v[162:163], v[52:53], v[16:17] op_sel_hi:[0,1,1]
	v_pk_fma_f32 v[18:19], v[162:163], v[56:57], v[18:19] op_sel_hi:[0,1,1]
	v_pk_fma_f32 v[20:21], v[162:163], v[60:61], v[20:21] op_sel_hi:[0,1,1]
	v_pk_fma_f32 v[22:23], v[162:163], v[64:65], v[22:23] op_sel_hi:[0,1,1]
	v_pk_fma_f32 v[24:25], v[162:163], v[68:69], v[24:25] op_sel_hi:[0,1,1]
	v_pk_fma_f32 v[26:27], v[162:163], v[72:73], v[26:27] op_sel_hi:[0,1,1]
	v_pk_fma_f32 v[28:29], v[162:163], v[76:77], v[28:29] op_sel_hi:[0,1,1]
	v_fmac_f32_e32 v41, v162, v79
	v_mov_b32_e32 v104, v103
	v_mov_b32_e32 v108, v107
	v_add_u32_e32 v9, 16, v9
	v_pk_fma_f32 v[14:15], v[164:165], v[30:31], v[14:15] op_sel_hi:[0,1,1]
	v_pk_fma_f32 v[16:17], v[164:165], v[32:33], v[16:17] op_sel_hi:[0,1,1]
	v_pk_fma_f32 v[18:19], v[164:165], v[74:75], v[18:19] op_sel_hi:[0,1,1]
	v_pk_fma_f32 v[20:21], v[164:165], v[82:83], v[20:21] op_sel_hi:[0,1,1]
	v_pk_fma_f32 v[22:23], v[164:165], v[86:87], v[22:23] op_sel_hi:[0,1,1]
	v_pk_fma_f32 v[24:25], v[164:165], v[90:91], v[24:25] op_sel_hi:[0,1,1]
	v_pk_fma_f32 v[26:27], v[164:165], v[94:95], v[26:27] op_sel_hi:[0,1,1]
	v_pk_fma_f32 v[28:29], v[164:165], v[98:99], v[28:29] op_sel_hi:[0,1,1]
	s_waitcnt lgkmcnt(0)
	v_fmac_f32_e32 v41, v164, v110
	v_pk_fma_f32 v[14:15], v[166:167], v[80:81], v[14:15] op_sel_hi:[0,1,1]
	v_pk_fma_f32 v[16:17], v[166:167], v[84:85], v[16:17] op_sel_hi:[0,1,1]
	v_pk_fma_f32 v[18:19], v[166:167], v[88:89], v[18:19] op_sel_hi:[0,1,1]
	v_pk_fma_f32 v[20:21], v[166:167], v[92:93], v[20:21] op_sel_hi:[0,1,1]
	v_pk_fma_f32 v[22:23], v[166:167], v[96:97], v[22:23] op_sel_hi:[0,1,1]
	v_pk_fma_f32 v[24:25], v[166:167], v[100:101], v[24:25] op_sel_hi:[0,1,1]
	v_pk_fma_f32 v[26:27], v[166:167], v[104:105], v[26:27] op_sel_hi:[0,1,1]
	v_pk_fma_f32 v[28:29], v[166:167], v[108:109], v[28:29] op_sel_hi:[0,1,1]
	v_fmac_f32_e32 v41, v166, v111
	v_add_u32_e32 v48, 0x1000, v9
	v_add_u32_e32 v50, 0x2000, v9
	v_add_u32_e32 v52, 0x3000, v9
	v_add_u32_e32 v54, 0x4000, v9
	v_add_u32_e32 v56, 0x5000, v9
	v_add_u32_e32 v58, 0x6000, v9
	v_add_u32_e32 v60, 0x7000, v9
	v_add_u32_e32 v62, 0x8000, v9
	v_add_u32_e32 v64, 0x9000, v9
	v_add_u32_e32 v66, 0xa000, v9
	v_add_u32_e32 v68, 0xb000, v9
	v_add_u32_e32 v70, 0xc000, v9
	ds_read2_b32 v[30:31], v9 offset1:1
	ds_read2_b32 v[32:33], v9 offset0:2 offset1:3
	v_add_u32_e32 v72, 0xd000, v9
	v_add_u32_e32 v74, 0xe000, v9
	v_add_u32_e32 v76, 0xf000, v9
	v_add_u32_e32 v78, 0x10000, v9
	ds_read2_b32 v[48:49], v48 offset1:1
	ds_read2_b32 v[50:51], v50 offset1:1
	ds_read2_b32 v[52:53], v52 offset1:1
	ds_read2_b32 v[54:55], v54 offset1:1
	ds_read2_b32 v[56:57], v56 offset1:1
	ds_read2_b32 v[58:59], v58 offset1:1
	ds_read2_b32 v[60:61], v60 offset1:1
	ds_read2_b32 v[62:63], v62 offset1:1
	ds_read2_b32 v[64:65], v64 offset1:1
	ds_read2_b32 v[66:67], v66 offset1:1
	ds_read2_b32 v[68:69], v68 offset1:1
	ds_read2_b32 v[70:71], v70 offset1:1
	v_add_u32_e32 v80, 0x1008, v9
	v_add_u32_e32 v82, 0x2008, v9
	v_add_u32_e32 v84, 0x3008, v9
	v_add_u32_e32 v86, 0x4008, v9
	v_add_u32_e32 v88, 0x5008, v9
	v_add_u32_e32 v90, 0x6008, v9
	v_add_u32_e32 v92, 0x7008, v9
	v_add_u32_e32 v94, 0x8008, v9
	v_add_u32_e32 v96, 0x9008, v9
	v_add_u32_e32 v98, 0xa008, v9
	v_add_u32_e32 v100, 0xb008, v9
	v_add_u32_e32 v102, 0xc008, v9
	ds_read2_b32 v[72:73], v72 offset1:1
	ds_read2_b32 v[74:75], v74 offset1:1
	ds_read2_b32 v[76:77], v76 offset1:1
	ds_read2_b32 v[78:79], v78 offset1:1
	ds_read2_b32 v[80:81], v80 offset1:1
	ds_read2_b32 v[82:83], v82 offset1:1
	ds_read2_b32 v[84:85], v84 offset1:1
	ds_read2_b32 v[86:87], v86 offset1:1
	ds_read2_b32 v[88:89], v88 offset1:1
	ds_read2_b32 v[90:91], v90 offset1:1
	ds_read2_b32 v[92:93], v92 offset1:1
	ds_read2_b32 v[94:95], v94 offset1:1
	ds_read2_b32 v[96:97], v96 offset1:1
	ds_read2_b32 v[98:99], v98 offset1:1
	ds_read2_b32 v[100:101], v100 offset1:1
	ds_read2_b32 v[102:103], v102 offset1:1
	v_add_u32_e32 v104, 0xd008, v9
	v_add_u32_e32 v106, 0xe008, v9
	v_add_u32_e32 v108, 0xf008, v9
	v_add_u32_e32 v110, 0x10008, v9
	ds_read2_b32 v[104:105], v104 offset1:1
	ds_read2_b32 v[106:107], v106 offset1:1
	ds_read2_b32 v[108:109], v108 offset1:1
	ds_read2_b32 v[110:111], v110 offset1:1
	s_waitcnt lgkmcnt(14)
	v_mov_b32_e32 v112, v30
	v_mov_b32_e32 v113, v48
	v_mov_b32_e32 v114, v50
	v_mov_b32_e32 v115, v52
	v_mov_b32_e32 v52, v51
	v_mov_b32_e32 v50, v54
	v_mov_b32_e32 v51, v56
	v_mov_b32_e32 v56, v55
	v_mov_b32_e32 v54, v58
	v_mov_b32_e32 v55, v60
	v_mov_b32_e32 v60, v59
	v_mov_b32_e32 v58, v62
	v_mov_b32_e32 v59, v64
	v_mov_b32_e32 v64, v63
	v_mov_b32_e32 v62, v66
	v_mov_b32_e32 v63, v68
	v_mov_b32_e32 v68, v67
	v_mov_b32_e32 v66, v70
	v_mov_b32_e32 v67, v72
	v_mov_b32_e32 v72, v71
	v_mov_b32_e32 v70, v74
	v_mov_b32_e32 v71, v76
	v_mov_b32_e32 v48, v31
	v_mov_b32_e32 v76, v75
	v_mov_b32_e32 v30, v32
	v_mov_b32_e32 v31, v80
	v_mov_b32_e32 v80, v33
	v_mov_b32_e32 v32, v82
	s_waitcnt lgkmcnt(13)
	v_mov_b32_e32 v33, v84
	v_mov_b32_e32 v84, v83
	s_waitcnt lgkmcnt(12)
	v_mov_b32_e32 v74, v86
	s_waitcnt lgkmcnt(11)
	v_mov_b32_e32 v75, v88
	v_mov_b32_e32 v88, v87
	s_waitcnt lgkmcnt(10)
	v_mov_b32_e32 v82, v90
	s_waitcnt lgkmcnt(9)
	v_mov_b32_e32 v83, v92
	v_mov_b32_e32 v92, v91
	s_waitcnt lgkmcnt(8)
	v_mov_b32_e32 v86, v94
	s_waitcnt lgkmcnt(7)
	v_mov_b32_e32 v87, v96
	v_mov_b32_e32 v96, v95
	s_waitcnt lgkmcnt(6)
	v_mov_b32_e32 v90, v98
	s_waitcnt lgkmcnt(5)
	v_mov_b32_e32 v91, v100
	v_mov_b32_e32 v100, v99
	s_waitcnt lgkmcnt(4)
	v_mov_b32_e32 v94, v102
	s_waitcnt lgkmcnt(3)
	v_mov_b32_e32 v95, v104
	s_waitcnt lgkmcnt(2)
	v_mov_b32_e32 v98, v106
	v_pk_fma_f32 v[14:15], v[168:169], v[112:113], v[14:15] op_sel_hi:[0,1,1]
	v_pk_fma_f32 v[16:17], v[168:169], v[114:115], v[16:17] op_sel_hi:[0,1,1]
	v_pk_fma_f32 v[18:19], v[168:169], v[50:51], v[18:19] op_sel_hi:[0,1,1]
	v_pk_fma_f32 v[20:21], v[168:169], v[54:55], v[20:21] op_sel_hi:[0,1,1]
	v_pk_fma_f32 v[22:23], v[168:169], v[58:59], v[22:23] op_sel_hi:[0,1,1]
	v_pk_fma_f32 v[24:25], v[168:169], v[62:63], v[24:25] op_sel_hi:[0,1,1]
	v_pk_fma_f32 v[26:27], v[168:169], v[66:67], v[26:27] op_sel_hi:[0,1,1]
	v_pk_fma_f32 v[28:29], v[168:169], v[70:71], v[28:29] op_sel_hi:[0,1,1]
	v_fmac_f32_e32 v41, v168, v78
	s_waitcnt lgkmcnt(1)
	v_mov_b32_e32 v99, v108
	v_pk_fma_f32 v[14:15], v[170:171], v[48:49], v[14:15] op_sel_hi:[0,1,1]
	v_pk_fma_f32 v[16:17], v[170:171], v[52:53], v[16:17] op_sel_hi:[0,1,1]
	v_pk_fma_f32 v[18:19], v[170:171], v[56:57], v[18:19] op_sel_hi:[0,1,1]
	v_pk_fma_f32 v[20:21], v[170:171], v[60:61], v[20:21] op_sel_hi:[0,1,1]
	v_pk_fma_f32 v[22:23], v[170:171], v[64:65], v[22:23] op_sel_hi:[0,1,1]
	v_pk_fma_f32 v[24:25], v[170:171], v[68:69], v[24:25] op_sel_hi:[0,1,1]
	v_pk_fma_f32 v[26:27], v[170:171], v[72:73], v[26:27] op_sel_hi:[0,1,1]
	v_pk_fma_f32 v[28:29], v[170:171], v[76:77], v[28:29] op_sel_hi:[0,1,1]
	v_fmac_f32_e32 v41, v170, v79
	v_mov_b32_e32 v104, v103
	v_mov_b32_e32 v108, v107
	v_add_u32_e32 v9, 16, v9
	v_pk_fma_f32 v[14:15], v[172:173], v[30:31], v[14:15] op_sel_hi:[0,1,1]
	v_pk_fma_f32 v[16:17], v[172:173], v[32:33], v[16:17] op_sel_hi:[0,1,1]
	v_pk_fma_f32 v[18:19], v[172:173], v[74:75], v[18:19] op_sel_hi:[0,1,1]
	v_pk_fma_f32 v[20:21], v[172:173], v[82:83], v[20:21] op_sel_hi:[0,1,1]
	v_pk_fma_f32 v[22:23], v[172:173], v[86:87], v[22:23] op_sel_hi:[0,1,1]
	v_pk_fma_f32 v[24:25], v[172:173], v[90:91], v[24:25] op_sel_hi:[0,1,1]
	v_pk_fma_f32 v[26:27], v[172:173], v[94:95], v[26:27] op_sel_hi:[0,1,1]
	v_pk_fma_f32 v[28:29], v[172:173], v[98:99], v[28:29] op_sel_hi:[0,1,1]
	s_waitcnt lgkmcnt(0)
	v_fmac_f32_e32 v41, v172, v110
	v_pk_fma_f32 v[14:15], v[174:175], v[80:81], v[14:15] op_sel_hi:[0,1,1]
	v_pk_fma_f32 v[16:17], v[174:175], v[84:85], v[16:17] op_sel_hi:[0,1,1]
	v_pk_fma_f32 v[18:19], v[174:175], v[88:89], v[18:19] op_sel_hi:[0,1,1]
	v_pk_fma_f32 v[20:21], v[174:175], v[92:93], v[20:21] op_sel_hi:[0,1,1]
	v_pk_fma_f32 v[22:23], v[174:175], v[96:97], v[22:23] op_sel_hi:[0,1,1]
	v_pk_fma_f32 v[24:25], v[174:175], v[100:101], v[24:25] op_sel_hi:[0,1,1]
	v_pk_fma_f32 v[26:27], v[174:175], v[104:105], v[26:27] op_sel_hi:[0,1,1]
	v_pk_fma_f32 v[28:29], v[174:175], v[108:109], v[28:29] op_sel_hi:[0,1,1]
	v_fmac_f32_e32 v41, v174, v111
	v_add_u32_e32 v48, 0x1000, v9
	v_add_u32_e32 v50, 0x2000, v9
	v_add_u32_e32 v52, 0x3000, v9
	v_add_u32_e32 v54, 0x4000, v9
	v_add_u32_e32 v56, 0x5000, v9
	v_add_u32_e32 v58, 0x6000, v9
	v_add_u32_e32 v60, 0x7000, v9
	v_add_u32_e32 v62, 0x8000, v9
	v_add_u32_e32 v64, 0x9000, v9
	v_add_u32_e32 v66, 0xa000, v9
	v_add_u32_e32 v68, 0xb000, v9
	v_add_u32_e32 v70, 0xc000, v9
	ds_read2_b32 v[30:31], v9 offset1:1
	ds_read2_b32 v[32:33], v9 offset0:2 offset1:3
	v_add_u32_e32 v72, 0xd000, v9
	v_add_u32_e32 v74, 0xe000, v9
	v_add_u32_e32 v76, 0xf000, v9
	v_add_u32_e32 v78, 0x10000, v9
	ds_read2_b32 v[48:49], v48 offset1:1
	ds_read2_b32 v[50:51], v50 offset1:1
	ds_read2_b32 v[52:53], v52 offset1:1
	ds_read2_b32 v[54:55], v54 offset1:1
	ds_read2_b32 v[56:57], v56 offset1:1
	ds_read2_b32 v[58:59], v58 offset1:1
	ds_read2_b32 v[60:61], v60 offset1:1
	ds_read2_b32 v[62:63], v62 offset1:1
	ds_read2_b32 v[64:65], v64 offset1:1
	ds_read2_b32 v[66:67], v66 offset1:1
	ds_read2_b32 v[68:69], v68 offset1:1
	ds_read2_b32 v[70:71], v70 offset1:1
	v_add_u32_e32 v80, 0x1008, v9
	v_add_u32_e32 v82, 0x2008, v9
	v_add_u32_e32 v84, 0x3008, v9
	v_add_u32_e32 v86, 0x4008, v9
	v_add_u32_e32 v88, 0x5008, v9
	v_add_u32_e32 v90, 0x6008, v9
	v_add_u32_e32 v92, 0x7008, v9
	v_add_u32_e32 v94, 0x8008, v9
	v_add_u32_e32 v96, 0x9008, v9
	v_add_u32_e32 v98, 0xa008, v9
	v_add_u32_e32 v100, 0xb008, v9
	v_add_u32_e32 v102, 0xc008, v9
	ds_read2_b32 v[72:73], v72 offset1:1
	ds_read2_b32 v[74:75], v74 offset1:1
	ds_read2_b32 v[76:77], v76 offset1:1
	ds_read2_b32 v[78:79], v78 offset1:1
	ds_read2_b32 v[80:81], v80 offset1:1
	ds_read2_b32 v[82:83], v82 offset1:1
	ds_read2_b32 v[84:85], v84 offset1:1
	ds_read2_b32 v[86:87], v86 offset1:1
	ds_read2_b32 v[88:89], v88 offset1:1
	ds_read2_b32 v[90:91], v90 offset1:1
	ds_read2_b32 v[92:93], v92 offset1:1
	ds_read2_b32 v[94:95], v94 offset1:1
	ds_read2_b32 v[96:97], v96 offset1:1
	ds_read2_b32 v[98:99], v98 offset1:1
	ds_read2_b32 v[100:101], v100 offset1:1
	ds_read2_b32 v[102:103], v102 offset1:1
	v_add_u32_e32 v104, 0xd008, v9
	v_add_u32_e32 v106, 0xe008, v9
	v_add_u32_e32 v108, 0xf008, v9
	v_add_u32_e32 v110, 0x10008, v9
	ds_read2_b32 v[104:105], v104 offset1:1
	ds_read2_b32 v[106:107], v106 offset1:1
	ds_read2_b32 v[108:109], v108 offset1:1
	ds_read2_b32 v[110:111], v110 offset1:1
	s_waitcnt lgkmcnt(14)
	v_mov_b32_e32 v112, v30
	v_mov_b32_e32 v113, v48
	v_mov_b32_e32 v114, v50
	v_mov_b32_e32 v115, v52
	v_mov_b32_e32 v52, v51
	v_mov_b32_e32 v50, v54
	v_mov_b32_e32 v51, v56
	v_mov_b32_e32 v56, v55
	v_mov_b32_e32 v54, v58
	v_mov_b32_e32 v55, v60
	v_mov_b32_e32 v60, v59
	v_mov_b32_e32 v58, v62
	v_mov_b32_e32 v59, v64
	v_mov_b32_e32 v64, v63
	v_mov_b32_e32 v62, v66
	v_mov_b32_e32 v63, v68
	v_mov_b32_e32 v68, v67
	v_mov_b32_e32 v66, v70
	v_mov_b32_e32 v67, v72
	v_mov_b32_e32 v72, v71
	v_mov_b32_e32 v70, v74
	v_mov_b32_e32 v71, v76
	v_mov_b32_e32 v48, v31
	v_mov_b32_e32 v76, v75
	v_mov_b32_e32 v30, v32
	v_mov_b32_e32 v31, v80
	v_mov_b32_e32 v80, v33
	v_mov_b32_e32 v32, v82
	s_waitcnt lgkmcnt(13)
	v_mov_b32_e32 v33, v84
	v_mov_b32_e32 v84, v83
	s_waitcnt lgkmcnt(12)
	v_mov_b32_e32 v74, v86
	s_waitcnt lgkmcnt(11)
	v_mov_b32_e32 v75, v88
	v_mov_b32_e32 v88, v87
	s_waitcnt lgkmcnt(10)
	v_mov_b32_e32 v82, v90
	s_waitcnt lgkmcnt(9)
	v_mov_b32_e32 v83, v92
	v_mov_b32_e32 v92, v91
	s_waitcnt lgkmcnt(8)
	v_mov_b32_e32 v86, v94
	s_waitcnt lgkmcnt(7)
	v_mov_b32_e32 v87, v96
	v_mov_b32_e32 v96, v95
	s_waitcnt lgkmcnt(6)
	v_mov_b32_e32 v90, v98
	s_waitcnt lgkmcnt(5)
	v_mov_b32_e32 v91, v100
	v_mov_b32_e32 v100, v99
	s_waitcnt lgkmcnt(4)
	v_mov_b32_e32 v94, v102
	s_waitcnt lgkmcnt(3)
	v_mov_b32_e32 v95, v104
	s_waitcnt lgkmcnt(2)
	v_mov_b32_e32 v98, v106
	v_pk_fma_f32 v[14:15], v[176:177], v[112:113], v[14:15] op_sel_hi:[0,1,1]
	v_pk_fma_f32 v[16:17], v[176:177], v[114:115], v[16:17] op_sel_hi:[0,1,1]
	v_pk_fma_f32 v[18:19], v[176:177], v[50:51], v[18:19] op_sel_hi:[0,1,1]
	v_pk_fma_f32 v[20:21], v[176:177], v[54:55], v[20:21] op_sel_hi:[0,1,1]
	v_pk_fma_f32 v[22:23], v[176:177], v[58:59], v[22:23] op_sel_hi:[0,1,1]
	v_pk_fma_f32 v[24:25], v[176:177], v[62:63], v[24:25] op_sel_hi:[0,1,1]
	v_pk_fma_f32 v[26:27], v[176:177], v[66:67], v[26:27] op_sel_hi:[0,1,1]
	v_pk_fma_f32 v[28:29], v[176:177], v[70:71], v[28:29] op_sel_hi:[0,1,1]
	v_fmac_f32_e32 v41, v176, v78
	s_waitcnt lgkmcnt(1)
	v_mov_b32_e32 v99, v108
	v_pk_fma_f32 v[14:15], v[178:179], v[48:49], v[14:15] op_sel_hi:[0,1,1]
	v_pk_fma_f32 v[16:17], v[178:179], v[52:53], v[16:17] op_sel_hi:[0,1,1]
	v_pk_fma_f32 v[18:19], v[178:179], v[56:57], v[18:19] op_sel_hi:[0,1,1]
	v_pk_fma_f32 v[20:21], v[178:179], v[60:61], v[20:21] op_sel_hi:[0,1,1]
	v_pk_fma_f32 v[22:23], v[178:179], v[64:65], v[22:23] op_sel_hi:[0,1,1]
	v_pk_fma_f32 v[24:25], v[178:179], v[68:69], v[24:25] op_sel_hi:[0,1,1]
	v_pk_fma_f32 v[26:27], v[178:179], v[72:73], v[26:27] op_sel_hi:[0,1,1]
	v_pk_fma_f32 v[28:29], v[178:179], v[76:77], v[28:29] op_sel_hi:[0,1,1]
	v_fmac_f32_e32 v41, v178, v79
	v_mov_b32_e32 v104, v103
	v_mov_b32_e32 v108, v107
	v_add_u32_e32 v9, 16, v9
	v_pk_fma_f32 v[14:15], v[180:181], v[30:31], v[14:15] op_sel_hi:[0,1,1]
	v_pk_fma_f32 v[16:17], v[180:181], v[32:33], v[16:17] op_sel_hi:[0,1,1]
	v_pk_fma_f32 v[18:19], v[180:181], v[74:75], v[18:19] op_sel_hi:[0,1,1]
	v_pk_fma_f32 v[20:21], v[180:181], v[82:83], v[20:21] op_sel_hi:[0,1,1]
	v_pk_fma_f32 v[22:23], v[180:181], v[86:87], v[22:23] op_sel_hi:[0,1,1]
	v_pk_fma_f32 v[24:25], v[180:181], v[90:91], v[24:25] op_sel_hi:[0,1,1]
	v_pk_fma_f32 v[26:27], v[180:181], v[94:95], v[26:27] op_sel_hi:[0,1,1]
	v_pk_fma_f32 v[28:29], v[180:181], v[98:99], v[28:29] op_sel_hi:[0,1,1]
	s_waitcnt lgkmcnt(0)
	v_fmac_f32_e32 v41, v180, v110
	v_pk_fma_f32 v[14:15], v[182:183], v[80:81], v[14:15] op_sel_hi:[0,1,1]
	v_pk_fma_f32 v[16:17], v[182:183], v[84:85], v[16:17] op_sel_hi:[0,1,1]
	v_pk_fma_f32 v[18:19], v[182:183], v[88:89], v[18:19] op_sel_hi:[0,1,1]
	v_pk_fma_f32 v[20:21], v[182:183], v[92:93], v[20:21] op_sel_hi:[0,1,1]
	v_pk_fma_f32 v[22:23], v[182:183], v[96:97], v[22:23] op_sel_hi:[0,1,1]
	v_pk_fma_f32 v[24:25], v[182:183], v[100:101], v[24:25] op_sel_hi:[0,1,1]
	v_pk_fma_f32 v[26:27], v[182:183], v[104:105], v[26:27] op_sel_hi:[0,1,1]
	v_pk_fma_f32 v[28:29], v[182:183], v[108:109], v[28:29] op_sel_hi:[0,1,1]
	v_fmac_f32_e32 v41, v182, v111
	v_add_u32_e32 v48, 0x1000, v9
	v_add_u32_e32 v50, 0x2000, v9
	v_add_u32_e32 v52, 0x3000, v9
	v_add_u32_e32 v54, 0x4000, v9
	v_add_u32_e32 v56, 0x5000, v9
	v_add_u32_e32 v58, 0x6000, v9
	v_add_u32_e32 v60, 0x7000, v9
	v_add_u32_e32 v62, 0x8000, v9
	v_add_u32_e32 v64, 0x9000, v9
	v_add_u32_e32 v66, 0xa000, v9
	v_add_u32_e32 v68, 0xb000, v9
	v_add_u32_e32 v70, 0xc000, v9
	ds_read2_b32 v[30:31], v9 offset1:1
	ds_read2_b32 v[32:33], v9 offset0:2 offset1:3
	v_add_u32_e32 v72, 0xd000, v9
	v_add_u32_e32 v74, 0xe000, v9
	v_add_u32_e32 v76, 0xf000, v9
	v_add_u32_e32 v78, 0x10000, v9
	ds_read2_b32 v[48:49], v48 offset1:1
	ds_read2_b32 v[50:51], v50 offset1:1
	ds_read2_b32 v[52:53], v52 offset1:1
	ds_read2_b32 v[54:55], v54 offset1:1
	ds_read2_b32 v[56:57], v56 offset1:1
	ds_read2_b32 v[58:59], v58 offset1:1
	ds_read2_b32 v[60:61], v60 offset1:1
	ds_read2_b32 v[62:63], v62 offset1:1
	ds_read2_b32 v[64:65], v64 offset1:1
	ds_read2_b32 v[66:67], v66 offset1:1
	ds_read2_b32 v[68:69], v68 offset1:1
	ds_read2_b32 v[70:71], v70 offset1:1
	v_add_u32_e32 v80, 0x1008, v9
	v_add_u32_e32 v82, 0x2008, v9
	v_add_u32_e32 v84, 0x3008, v9
	v_add_u32_e32 v86, 0x4008, v9
	v_add_u32_e32 v88, 0x5008, v9
	v_add_u32_e32 v90, 0x6008, v9
	v_add_u32_e32 v92, 0x7008, v9
	v_add_u32_e32 v94, 0x8008, v9
	v_add_u32_e32 v96, 0x9008, v9
	v_add_u32_e32 v98, 0xa008, v9
	v_add_u32_e32 v100, 0xb008, v9
	v_add_u32_e32 v102, 0xc008, v9
	ds_read2_b32 v[72:73], v72 offset1:1
	ds_read2_b32 v[74:75], v74 offset1:1
	ds_read2_b32 v[76:77], v76 offset1:1
	ds_read2_b32 v[78:79], v78 offset1:1
	ds_read2_b32 v[80:81], v80 offset1:1
	ds_read2_b32 v[82:83], v82 offset1:1
	ds_read2_b32 v[84:85], v84 offset1:1
	ds_read2_b32 v[86:87], v86 offset1:1
	ds_read2_b32 v[88:89], v88 offset1:1
	ds_read2_b32 v[90:91], v90 offset1:1
	ds_read2_b32 v[92:93], v92 offset1:1
	ds_read2_b32 v[94:95], v94 offset1:1
	ds_read2_b32 v[96:97], v96 offset1:1
	ds_read2_b32 v[98:99], v98 offset1:1
	ds_read2_b32 v[100:101], v100 offset1:1
	ds_read2_b32 v[102:103], v102 offset1:1
	v_add_u32_e32 v104, 0xd008, v9
	v_add_u32_e32 v106, 0xe008, v9
	v_add_u32_e32 v108, 0xf008, v9
	v_add_u32_e32 v110, 0x10008, v9
	ds_read2_b32 v[104:105], v104 offset1:1
	ds_read2_b32 v[106:107], v106 offset1:1
	ds_read2_b32 v[108:109], v108 offset1:1
	ds_read2_b32 v[110:111], v110 offset1:1
	s_waitcnt lgkmcnt(14)
	v_mov_b32_e32 v112, v30
	v_mov_b32_e32 v113, v48
	v_mov_b32_e32 v114, v50
	v_mov_b32_e32 v115, v52
	v_mov_b32_e32 v52, v51
	v_mov_b32_e32 v50, v54
	v_mov_b32_e32 v51, v56
	v_mov_b32_e32 v56, v55
	v_mov_b32_e32 v54, v58
	v_mov_b32_e32 v55, v60
	v_mov_b32_e32 v60, v59
	v_mov_b32_e32 v58, v62
	v_mov_b32_e32 v59, v64
	v_mov_b32_e32 v64, v63
	v_mov_b32_e32 v62, v66
	v_mov_b32_e32 v63, v68
	v_mov_b32_e32 v68, v67
	v_mov_b32_e32 v66, v70
	v_mov_b32_e32 v67, v72
	v_mov_b32_e32 v72, v71
	v_mov_b32_e32 v70, v74
	v_mov_b32_e32 v71, v76
	v_mov_b32_e32 v48, v31
	v_mov_b32_e32 v76, v75
	v_mov_b32_e32 v30, v32
	v_mov_b32_e32 v31, v80
	v_mov_b32_e32 v80, v33
	v_mov_b32_e32 v32, v82
	s_waitcnt lgkmcnt(13)
	v_mov_b32_e32 v33, v84
	v_mov_b32_e32 v84, v83
	s_waitcnt lgkmcnt(12)
	v_mov_b32_e32 v74, v86
	s_waitcnt lgkmcnt(11)
	v_mov_b32_e32 v75, v88
	v_mov_b32_e32 v88, v87
	s_waitcnt lgkmcnt(10)
	v_mov_b32_e32 v82, v90
	s_waitcnt lgkmcnt(9)
	v_mov_b32_e32 v83, v92
	v_mov_b32_e32 v92, v91
	s_waitcnt lgkmcnt(8)
	v_mov_b32_e32 v86, v94
	s_waitcnt lgkmcnt(7)
	v_mov_b32_e32 v87, v96
	v_mov_b32_e32 v96, v95
	s_waitcnt lgkmcnt(6)
	v_mov_b32_e32 v90, v98
	s_waitcnt lgkmcnt(5)
	v_mov_b32_e32 v91, v100
	v_mov_b32_e32 v100, v99
	s_waitcnt lgkmcnt(4)
	v_mov_b32_e32 v94, v102
	s_waitcnt lgkmcnt(3)
	v_mov_b32_e32 v95, v104
	s_waitcnt lgkmcnt(2)
	v_mov_b32_e32 v98, v106
	v_pk_fma_f32 v[14:15], v[184:185], v[112:113], v[14:15] op_sel_hi:[0,1,1]
	v_pk_fma_f32 v[16:17], v[184:185], v[114:115], v[16:17] op_sel_hi:[0,1,1]
	v_pk_fma_f32 v[18:19], v[184:185], v[50:51], v[18:19] op_sel_hi:[0,1,1]
	v_pk_fma_f32 v[20:21], v[184:185], v[54:55], v[20:21] op_sel_hi:[0,1,1]
	v_pk_fma_f32 v[22:23], v[184:185], v[58:59], v[22:23] op_sel_hi:[0,1,1]
	v_pk_fma_f32 v[24:25], v[184:185], v[62:63], v[24:25] op_sel_hi:[0,1,1]
	v_pk_fma_f32 v[26:27], v[184:185], v[66:67], v[26:27] op_sel_hi:[0,1,1]
	v_pk_fma_f32 v[28:29], v[184:185], v[70:71], v[28:29] op_sel_hi:[0,1,1]
	v_fmac_f32_e32 v41, v184, v78
	s_waitcnt lgkmcnt(1)
	v_mov_b32_e32 v99, v108
	v_pk_fma_f32 v[14:15], v[186:187], v[48:49], v[14:15] op_sel_hi:[0,1,1]
	v_pk_fma_f32 v[16:17], v[186:187], v[52:53], v[16:17] op_sel_hi:[0,1,1]
	v_pk_fma_f32 v[18:19], v[186:187], v[56:57], v[18:19] op_sel_hi:[0,1,1]
	v_pk_fma_f32 v[20:21], v[186:187], v[60:61], v[20:21] op_sel_hi:[0,1,1]
	v_pk_fma_f32 v[22:23], v[186:187], v[64:65], v[22:23] op_sel_hi:[0,1,1]
	v_pk_fma_f32 v[24:25], v[186:187], v[68:69], v[24:25] op_sel_hi:[0,1,1]
	v_pk_fma_f32 v[26:27], v[186:187], v[72:73], v[26:27] op_sel_hi:[0,1,1]
	v_pk_fma_f32 v[28:29], v[186:187], v[76:77], v[28:29] op_sel_hi:[0,1,1]
	v_fmac_f32_e32 v41, v186, v79
	v_mov_b32_e32 v104, v103
	v_mov_b32_e32 v108, v107
	v_add_u32_e32 v9, 16, v9
	v_pk_fma_f32 v[14:15], v[188:189], v[30:31], v[14:15] op_sel_hi:[0,1,1]
	v_pk_fma_f32 v[16:17], v[188:189], v[32:33], v[16:17] op_sel_hi:[0,1,1]
	v_pk_fma_f32 v[18:19], v[188:189], v[74:75], v[18:19] op_sel_hi:[0,1,1]
	v_pk_fma_f32 v[20:21], v[188:189], v[82:83], v[20:21] op_sel_hi:[0,1,1]
	v_pk_fma_f32 v[22:23], v[188:189], v[86:87], v[22:23] op_sel_hi:[0,1,1]
	v_pk_fma_f32 v[24:25], v[188:189], v[90:91], v[24:25] op_sel_hi:[0,1,1]
	v_pk_fma_f32 v[26:27], v[188:189], v[94:95], v[26:27] op_sel_hi:[0,1,1]
	v_pk_fma_f32 v[28:29], v[188:189], v[98:99], v[28:29] op_sel_hi:[0,1,1]
	s_waitcnt lgkmcnt(0)
	v_fmac_f32_e32 v41, v188, v110
	v_pk_fma_f32 v[14:15], v[190:191], v[80:81], v[14:15] op_sel_hi:[0,1,1]
	v_pk_fma_f32 v[16:17], v[190:191], v[84:85], v[16:17] op_sel_hi:[0,1,1]
	v_pk_fma_f32 v[18:19], v[190:191], v[88:89], v[18:19] op_sel_hi:[0,1,1]
	v_pk_fma_f32 v[20:21], v[190:191], v[92:93], v[20:21] op_sel_hi:[0,1,1]
	v_pk_fma_f32 v[22:23], v[190:191], v[96:97], v[22:23] op_sel_hi:[0,1,1]
	v_pk_fma_f32 v[24:25], v[190:191], v[100:101], v[24:25] op_sel_hi:[0,1,1]
	v_pk_fma_f32 v[26:27], v[190:191], v[104:105], v[26:27] op_sel_hi:[0,1,1]
	v_pk_fma_f32 v[28:29], v[190:191], v[108:109], v[28:29] op_sel_hi:[0,1,1]
	v_fmac_f32_e32 v41, v190, v111
	v_add_u32_e32 v48, 0x1000, v9
	v_add_u32_e32 v50, 0x2000, v9
	v_add_u32_e32 v52, 0x3000, v9
	v_add_u32_e32 v54, 0x4000, v9
	v_add_u32_e32 v56, 0x5000, v9
	v_add_u32_e32 v58, 0x6000, v9
	v_add_u32_e32 v60, 0x7000, v9
	v_add_u32_e32 v62, 0x8000, v9
	v_add_u32_e32 v64, 0x9000, v9
	v_add_u32_e32 v66, 0xa000, v9
	v_add_u32_e32 v68, 0xb000, v9
	v_add_u32_e32 v70, 0xc000, v9
	ds_read2_b32 v[30:31], v9 offset1:1
	ds_read2_b32 v[32:33], v9 offset0:2 offset1:3
	v_add_u32_e32 v72, 0xd000, v9
	v_add_u32_e32 v74, 0xe000, v9
	v_add_u32_e32 v76, 0xf000, v9
	v_add_u32_e32 v78, 0x10000, v9
	ds_read2_b32 v[48:49], v48 offset1:1
	ds_read2_b32 v[50:51], v50 offset1:1
	ds_read2_b32 v[52:53], v52 offset1:1
	ds_read2_b32 v[54:55], v54 offset1:1
	ds_read2_b32 v[56:57], v56 offset1:1
	ds_read2_b32 v[58:59], v58 offset1:1
	ds_read2_b32 v[60:61], v60 offset1:1
	ds_read2_b32 v[62:63], v62 offset1:1
	ds_read2_b32 v[64:65], v64 offset1:1
	ds_read2_b32 v[66:67], v66 offset1:1
	ds_read2_b32 v[68:69], v68 offset1:1
	ds_read2_b32 v[70:71], v70 offset1:1
	v_add_u32_e32 v80, 0x1008, v9
	v_add_u32_e32 v82, 0x2008, v9
	v_add_u32_e32 v84, 0x3008, v9
	v_add_u32_e32 v86, 0x4008, v9
	v_add_u32_e32 v88, 0x5008, v9
	v_add_u32_e32 v90, 0x6008, v9
	v_add_u32_e32 v92, 0x7008, v9
	v_add_u32_e32 v94, 0x8008, v9
	v_add_u32_e32 v96, 0x9008, v9
	v_add_u32_e32 v98, 0xa008, v9
	v_add_u32_e32 v100, 0xb008, v9
	v_add_u32_e32 v102, 0xc008, v9
	ds_read2_b32 v[72:73], v72 offset1:1
	ds_read2_b32 v[74:75], v74 offset1:1
	ds_read2_b32 v[76:77], v76 offset1:1
	ds_read2_b32 v[78:79], v78 offset1:1
	ds_read2_b32 v[80:81], v80 offset1:1
	ds_read2_b32 v[82:83], v82 offset1:1
	ds_read2_b32 v[84:85], v84 offset1:1
	ds_read2_b32 v[86:87], v86 offset1:1
	ds_read2_b32 v[88:89], v88 offset1:1
	ds_read2_b32 v[90:91], v90 offset1:1
	ds_read2_b32 v[92:93], v92 offset1:1
	ds_read2_b32 v[94:95], v94 offset1:1
	ds_read2_b32 v[96:97], v96 offset1:1
	ds_read2_b32 v[98:99], v98 offset1:1
	ds_read2_b32 v[100:101], v100 offset1:1
	ds_read2_b32 v[102:103], v102 offset1:1
	v_add_u32_e32 v104, 0xd008, v9
	v_add_u32_e32 v106, 0xe008, v9
	v_add_u32_e32 v108, 0xf008, v9
	v_add_u32_e32 v110, 0x10008, v9
	ds_read2_b32 v[104:105], v104 offset1:1
	ds_read2_b32 v[106:107], v106 offset1:1
	ds_read2_b32 v[108:109], v108 offset1:1
	ds_read2_b32 v[110:111], v110 offset1:1
	s_waitcnt lgkmcnt(14)
	v_mov_b32_e32 v112, v30
	v_mov_b32_e32 v113, v48
	v_mov_b32_e32 v114, v50
	v_mov_b32_e32 v115, v52
	v_mov_b32_e32 v52, v51
	v_mov_b32_e32 v50, v54
	v_mov_b32_e32 v51, v56
	v_mov_b32_e32 v56, v55
	v_mov_b32_e32 v54, v58
	v_mov_b32_e32 v55, v60
	v_mov_b32_e32 v60, v59
	v_mov_b32_e32 v58, v62
	v_mov_b32_e32 v59, v64
	v_mov_b32_e32 v64, v63
	v_mov_b32_e32 v62, v66
	v_mov_b32_e32 v63, v68
	v_mov_b32_e32 v68, v67
	v_mov_b32_e32 v66, v70
	v_mov_b32_e32 v67, v72
	v_mov_b32_e32 v72, v71
	v_mov_b32_e32 v70, v74
	v_mov_b32_e32 v71, v76
	v_mov_b32_e32 v48, v31
	v_mov_b32_e32 v76, v75
	v_mov_b32_e32 v30, v32
	v_mov_b32_e32 v31, v80
	v_mov_b32_e32 v80, v33
	v_mov_b32_e32 v32, v82
	s_waitcnt lgkmcnt(13)
	v_mov_b32_e32 v33, v84
	v_mov_b32_e32 v84, v83
	s_waitcnt lgkmcnt(12)
	v_mov_b32_e32 v74, v86
	s_waitcnt lgkmcnt(11)
	v_mov_b32_e32 v75, v88
	v_mov_b32_e32 v88, v87
	s_waitcnt lgkmcnt(10)
	v_mov_b32_e32 v82, v90
	s_waitcnt lgkmcnt(9)
	v_mov_b32_e32 v83, v92
	v_mov_b32_e32 v92, v91
	s_waitcnt lgkmcnt(8)
	v_mov_b32_e32 v86, v94
	s_waitcnt lgkmcnt(7)
	v_mov_b32_e32 v87, v96
	v_mov_b32_e32 v96, v95
	s_waitcnt lgkmcnt(6)
	v_mov_b32_e32 v90, v98
	s_waitcnt lgkmcnt(5)
	v_mov_b32_e32 v91, v100
	v_mov_b32_e32 v100, v99
	s_waitcnt lgkmcnt(4)
	v_mov_b32_e32 v94, v102
	s_waitcnt lgkmcnt(3)
	v_mov_b32_e32 v95, v104
	s_waitcnt lgkmcnt(2)
	v_mov_b32_e32 v98, v106
	v_pk_fma_f32 v[14:15], v[192:193], v[112:113], v[14:15] op_sel_hi:[0,1,1]
	v_pk_fma_f32 v[16:17], v[192:193], v[114:115], v[16:17] op_sel_hi:[0,1,1]
	v_pk_fma_f32 v[18:19], v[192:193], v[50:51], v[18:19] op_sel_hi:[0,1,1]
	v_pk_fma_f32 v[20:21], v[192:193], v[54:55], v[20:21] op_sel_hi:[0,1,1]
	v_pk_fma_f32 v[22:23], v[192:193], v[58:59], v[22:23] op_sel_hi:[0,1,1]
	v_pk_fma_f32 v[24:25], v[192:193], v[62:63], v[24:25] op_sel_hi:[0,1,1]
	v_pk_fma_f32 v[26:27], v[192:193], v[66:67], v[26:27] op_sel_hi:[0,1,1]
	v_pk_fma_f32 v[28:29], v[192:193], v[70:71], v[28:29] op_sel_hi:[0,1,1]
	v_fmac_f32_e32 v41, v192, v78
	s_waitcnt lgkmcnt(1)
	v_mov_b32_e32 v99, v108
	v_pk_fma_f32 v[14:15], v[194:195], v[48:49], v[14:15] op_sel_hi:[0,1,1]
	v_pk_fma_f32 v[16:17], v[194:195], v[52:53], v[16:17] op_sel_hi:[0,1,1]
	v_pk_fma_f32 v[18:19], v[194:195], v[56:57], v[18:19] op_sel_hi:[0,1,1]
	v_pk_fma_f32 v[20:21], v[194:195], v[60:61], v[20:21] op_sel_hi:[0,1,1]
	v_pk_fma_f32 v[22:23], v[194:195], v[64:65], v[22:23] op_sel_hi:[0,1,1]
	v_pk_fma_f32 v[24:25], v[194:195], v[68:69], v[24:25] op_sel_hi:[0,1,1]
	v_pk_fma_f32 v[26:27], v[194:195], v[72:73], v[26:27] op_sel_hi:[0,1,1]
	v_pk_fma_f32 v[28:29], v[194:195], v[76:77], v[28:29] op_sel_hi:[0,1,1]
	v_fmac_f32_e32 v41, v194, v79
	v_mov_b32_e32 v104, v103
	v_mov_b32_e32 v108, v107
	v_add_u32_e32 v9, 16, v9
	v_pk_fma_f32 v[14:15], v[196:197], v[30:31], v[14:15] op_sel_hi:[0,1,1]
	v_pk_fma_f32 v[16:17], v[196:197], v[32:33], v[16:17] op_sel_hi:[0,1,1]
	v_pk_fma_f32 v[18:19], v[196:197], v[74:75], v[18:19] op_sel_hi:[0,1,1]
	v_pk_fma_f32 v[20:21], v[196:197], v[82:83], v[20:21] op_sel_hi:[0,1,1]
	v_pk_fma_f32 v[22:23], v[196:197], v[86:87], v[22:23] op_sel_hi:[0,1,1]
	v_pk_fma_f32 v[24:25], v[196:197], v[90:91], v[24:25] op_sel_hi:[0,1,1]
	v_pk_fma_f32 v[26:27], v[196:197], v[94:95], v[26:27] op_sel_hi:[0,1,1]
	v_pk_fma_f32 v[28:29], v[196:197], v[98:99], v[28:29] op_sel_hi:[0,1,1]
	s_waitcnt lgkmcnt(0)
	v_fmac_f32_e32 v41, v196, v110
	v_pk_fma_f32 v[14:15], v[200:201], v[80:81], v[14:15] op_sel_hi:[0,1,1]
	v_pk_fma_f32 v[16:17], v[200:201], v[84:85], v[16:17] op_sel_hi:[0,1,1]
	v_pk_fma_f32 v[18:19], v[200:201], v[88:89], v[18:19] op_sel_hi:[0,1,1]
	v_pk_fma_f32 v[20:21], v[200:201], v[92:93], v[20:21] op_sel_hi:[0,1,1]
	v_pk_fma_f32 v[22:23], v[200:201], v[96:97], v[22:23] op_sel_hi:[0,1,1]
	v_pk_fma_f32 v[24:25], v[200:201], v[100:101], v[24:25] op_sel_hi:[0,1,1]
	v_pk_fma_f32 v[26:27], v[200:201], v[104:105], v[26:27] op_sel_hi:[0,1,1]
	v_pk_fma_f32 v[28:29], v[200:201], v[108:109], v[28:29] op_sel_hi:[0,1,1]
	v_fmac_f32_e32 v41, v200, v111
	v_add_u32_e32 v48, 0x1000, v9
	v_add_u32_e32 v50, 0x2000, v9
	v_add_u32_e32 v52, 0x3000, v9
	v_add_u32_e32 v54, 0x4000, v9
	v_add_u32_e32 v56, 0x5000, v9
	v_add_u32_e32 v58, 0x6000, v9
	v_add_u32_e32 v60, 0x7000, v9
	v_add_u32_e32 v62, 0x8000, v9
	v_add_u32_e32 v64, 0x9000, v9
	v_add_u32_e32 v66, 0xa000, v9
	v_add_u32_e32 v68, 0xb000, v9
	v_add_u32_e32 v70, 0xc000, v9
	ds_read2_b32 v[30:31], v9 offset1:1
	ds_read2_b32 v[32:33], v9 offset0:2 offset1:3
	v_add_u32_e32 v72, 0xd000, v9
	v_add_u32_e32 v74, 0xe000, v9
	v_add_u32_e32 v76, 0xf000, v9
	v_add_u32_e32 v78, 0x10000, v9
	ds_read2_b32 v[48:49], v48 offset1:1
	ds_read2_b32 v[50:51], v50 offset1:1
	ds_read2_b32 v[52:53], v52 offset1:1
	ds_read2_b32 v[54:55], v54 offset1:1
	ds_read2_b32 v[56:57], v56 offset1:1
	ds_read2_b32 v[58:59], v58 offset1:1
	ds_read2_b32 v[60:61], v60 offset1:1
	ds_read2_b32 v[62:63], v62 offset1:1
	ds_read2_b32 v[64:65], v64 offset1:1
	ds_read2_b32 v[66:67], v66 offset1:1
	ds_read2_b32 v[68:69], v68 offset1:1
	ds_read2_b32 v[70:71], v70 offset1:1
	v_add_u32_e32 v80, 0x1008, v9
	v_add_u32_e32 v82, 0x2008, v9
	v_add_u32_e32 v84, 0x3008, v9
	v_add_u32_e32 v86, 0x4008, v9
	v_add_u32_e32 v88, 0x5008, v9
	v_add_u32_e32 v90, 0x6008, v9
	v_add_u32_e32 v92, 0x7008, v9
	v_add_u32_e32 v94, 0x8008, v9
	v_add_u32_e32 v96, 0x9008, v9
	v_add_u32_e32 v98, 0xa008, v9
	v_add_u32_e32 v100, 0xb008, v9
	v_add_u32_e32 v102, 0xc008, v9
	ds_read2_b32 v[72:73], v72 offset1:1
	ds_read2_b32 v[74:75], v74 offset1:1
	ds_read2_b32 v[76:77], v76 offset1:1
	ds_read2_b32 v[78:79], v78 offset1:1
	ds_read2_b32 v[80:81], v80 offset1:1
	ds_read2_b32 v[82:83], v82 offset1:1
	ds_read2_b32 v[84:85], v84 offset1:1
	ds_read2_b32 v[86:87], v86 offset1:1
	ds_read2_b32 v[88:89], v88 offset1:1
	ds_read2_b32 v[90:91], v90 offset1:1
	ds_read2_b32 v[92:93], v92 offset1:1
	ds_read2_b32 v[94:95], v94 offset1:1
	ds_read2_b32 v[96:97], v96 offset1:1
	ds_read2_b32 v[98:99], v98 offset1:1
	ds_read2_b32 v[100:101], v100 offset1:1
	ds_read2_b32 v[102:103], v102 offset1:1
	v_add_u32_e32 v104, 0xd008, v9
	v_add_u32_e32 v106, 0xe008, v9
	v_add_u32_e32 v108, 0xf008, v9
	v_add_u32_e32 v110, 0x10008, v9
	ds_read2_b32 v[104:105], v104 offset1:1
	ds_read2_b32 v[106:107], v106 offset1:1
	ds_read2_b32 v[108:109], v108 offset1:1
	ds_read2_b32 v[110:111], v110 offset1:1
	s_waitcnt lgkmcnt(14)
	v_mov_b32_e32 v112, v30
	v_mov_b32_e32 v113, v48
	v_mov_b32_e32 v114, v50
	v_mov_b32_e32 v115, v52
	v_mov_b32_e32 v52, v51
	v_mov_b32_e32 v50, v54
	v_mov_b32_e32 v51, v56
	v_mov_b32_e32 v56, v55
	v_mov_b32_e32 v54, v58
	v_mov_b32_e32 v55, v60
	v_mov_b32_e32 v60, v59
	v_mov_b32_e32 v58, v62
	v_mov_b32_e32 v59, v64
	v_mov_b32_e32 v64, v63
	v_mov_b32_e32 v62, v66
	v_mov_b32_e32 v63, v68
	v_mov_b32_e32 v68, v67
	v_mov_b32_e32 v66, v70
	v_mov_b32_e32 v67, v72
	v_mov_b32_e32 v72, v71
	v_mov_b32_e32 v70, v74
	v_mov_b32_e32 v71, v76
	v_mov_b32_e32 v48, v31
	v_mov_b32_e32 v76, v75
	v_mov_b32_e32 v30, v32
	v_mov_b32_e32 v31, v80
	v_mov_b32_e32 v80, v33
	v_mov_b32_e32 v32, v82
	s_waitcnt lgkmcnt(13)
	v_mov_b32_e32 v33, v84
	v_mov_b32_e32 v84, v83
	s_waitcnt lgkmcnt(12)
	v_mov_b32_e32 v74, v86
	s_waitcnt lgkmcnt(11)
	v_mov_b32_e32 v75, v88
	v_mov_b32_e32 v88, v87
	s_waitcnt lgkmcnt(10)
	v_mov_b32_e32 v82, v90
	s_waitcnt lgkmcnt(9)
	v_mov_b32_e32 v83, v92
	v_mov_b32_e32 v92, v91
	s_waitcnt lgkmcnt(8)
	v_mov_b32_e32 v86, v94
	s_waitcnt lgkmcnt(7)
	v_mov_b32_e32 v87, v96
	v_mov_b32_e32 v96, v95
	s_waitcnt lgkmcnt(6)
	v_mov_b32_e32 v90, v98
	s_waitcnt lgkmcnt(5)
	v_mov_b32_e32 v91, v100
	v_mov_b32_e32 v100, v99
	s_waitcnt lgkmcnt(4)
	v_mov_b32_e32 v94, v102
	s_waitcnt lgkmcnt(3)
	v_mov_b32_e32 v95, v104
	s_waitcnt lgkmcnt(2)
	v_mov_b32_e32 v98, v106
	v_pk_fma_f32 v[14:15], v[202:203], v[112:113], v[14:15] op_sel_hi:[0,1,1]
	v_pk_fma_f32 v[16:17], v[202:203], v[114:115], v[16:17] op_sel_hi:[0,1,1]
	v_pk_fma_f32 v[18:19], v[202:203], v[50:51], v[18:19] op_sel_hi:[0,1,1]
	v_pk_fma_f32 v[20:21], v[202:203], v[54:55], v[20:21] op_sel_hi:[0,1,1]
	v_pk_fma_f32 v[22:23], v[202:203], v[58:59], v[22:23] op_sel_hi:[0,1,1]
	v_pk_fma_f32 v[24:25], v[202:203], v[62:63], v[24:25] op_sel_hi:[0,1,1]
	v_pk_fma_f32 v[26:27], v[202:203], v[66:67], v[26:27] op_sel_hi:[0,1,1]
	v_pk_fma_f32 v[28:29], v[202:203], v[70:71], v[28:29] op_sel_hi:[0,1,1]
	v_fmac_f32_e32 v41, v202, v78
	s_waitcnt lgkmcnt(1)
	v_mov_b32_e32 v99, v108
	v_pk_fma_f32 v[14:15], v[204:205], v[48:49], v[14:15] op_sel_hi:[0,1,1]
	v_pk_fma_f32 v[16:17], v[204:205], v[52:53], v[16:17] op_sel_hi:[0,1,1]
	v_pk_fma_f32 v[18:19], v[204:205], v[56:57], v[18:19] op_sel_hi:[0,1,1]
	v_pk_fma_f32 v[20:21], v[204:205], v[60:61], v[20:21] op_sel_hi:[0,1,1]
	v_pk_fma_f32 v[22:23], v[204:205], v[64:65], v[22:23] op_sel_hi:[0,1,1]
	v_pk_fma_f32 v[24:25], v[204:205], v[68:69], v[24:25] op_sel_hi:[0,1,1]
	v_pk_fma_f32 v[26:27], v[204:205], v[72:73], v[26:27] op_sel_hi:[0,1,1]
	v_pk_fma_f32 v[28:29], v[204:205], v[76:77], v[28:29] op_sel_hi:[0,1,1]
	v_fmac_f32_e32 v41, v204, v79
	v_mov_b32_e32 v104, v103
	v_mov_b32_e32 v108, v107
	v_add_u32_e32 v9, 16, v9
	v_pk_fma_f32 v[14:15], v[206:207], v[30:31], v[14:15] op_sel_hi:[0,1,1]
	v_pk_fma_f32 v[16:17], v[206:207], v[32:33], v[16:17] op_sel_hi:[0,1,1]
	v_pk_fma_f32 v[18:19], v[206:207], v[74:75], v[18:19] op_sel_hi:[0,1,1]
	v_pk_fma_f32 v[20:21], v[206:207], v[82:83], v[20:21] op_sel_hi:[0,1,1]
	v_pk_fma_f32 v[22:23], v[206:207], v[86:87], v[22:23] op_sel_hi:[0,1,1]
	v_pk_fma_f32 v[24:25], v[206:207], v[90:91], v[24:25] op_sel_hi:[0,1,1]
	v_pk_fma_f32 v[26:27], v[206:207], v[94:95], v[26:27] op_sel_hi:[0,1,1]
	v_pk_fma_f32 v[28:29], v[206:207], v[98:99], v[28:29] op_sel_hi:[0,1,1]
	s_waitcnt lgkmcnt(0)
	v_fmac_f32_e32 v41, v206, v110
	v_pk_fma_f32 v[14:15], v[208:209], v[80:81], v[14:15] op_sel_hi:[0,1,1]
	v_pk_fma_f32 v[16:17], v[208:209], v[84:85], v[16:17] op_sel_hi:[0,1,1]
	v_pk_fma_f32 v[18:19], v[208:209], v[88:89], v[18:19] op_sel_hi:[0,1,1]
	v_pk_fma_f32 v[20:21], v[208:209], v[92:93], v[20:21] op_sel_hi:[0,1,1]
	v_pk_fma_f32 v[22:23], v[208:209], v[96:97], v[22:23] op_sel_hi:[0,1,1]
	v_pk_fma_f32 v[24:25], v[208:209], v[100:101], v[24:25] op_sel_hi:[0,1,1]
	v_pk_fma_f32 v[26:27], v[208:209], v[104:105], v[26:27] op_sel_hi:[0,1,1]
	v_pk_fma_f32 v[28:29], v[208:209], v[108:109], v[28:29] op_sel_hi:[0,1,1]
	v_fmac_f32_e32 v41, v208, v111
	v_add_u32_e32 v48, 0x1000, v9
	v_add_u32_e32 v50, 0x2000, v9
	v_add_u32_e32 v52, 0x3000, v9
	v_add_u32_e32 v54, 0x4000, v9
	v_add_u32_e32 v56, 0x5000, v9
	v_add_u32_e32 v58, 0x6000, v9
	v_add_u32_e32 v60, 0x7000, v9
	v_add_u32_e32 v62, 0x8000, v9
	v_add_u32_e32 v64, 0x9000, v9
	v_add_u32_e32 v66, 0xa000, v9
	v_add_u32_e32 v68, 0xb000, v9
	v_add_u32_e32 v70, 0xc000, v9
	ds_read2_b32 v[30:31], v9 offset1:1
	ds_read2_b32 v[32:33], v9 offset0:2 offset1:3
	v_add_u32_e32 v72, 0xd000, v9
	v_add_u32_e32 v74, 0xe000, v9
	v_add_u32_e32 v76, 0xf000, v9
	v_add_u32_e32 v78, 0x10000, v9
	ds_read2_b32 v[48:49], v48 offset1:1
	ds_read2_b32 v[50:51], v50 offset1:1
	ds_read2_b32 v[52:53], v52 offset1:1
	ds_read2_b32 v[54:55], v54 offset1:1
	ds_read2_b32 v[56:57], v56 offset1:1
	ds_read2_b32 v[58:59], v58 offset1:1
	ds_read2_b32 v[60:61], v60 offset1:1
	ds_read2_b32 v[62:63], v62 offset1:1
	ds_read2_b32 v[64:65], v64 offset1:1
	ds_read2_b32 v[66:67], v66 offset1:1
	ds_read2_b32 v[68:69], v68 offset1:1
	ds_read2_b32 v[70:71], v70 offset1:1
	v_add_u32_e32 v80, 0x1008, v9
	v_add_u32_e32 v82, 0x2008, v9
	v_add_u32_e32 v84, 0x3008, v9
	v_add_u32_e32 v86, 0x4008, v9
	v_add_u32_e32 v88, 0x5008, v9
	v_add_u32_e32 v90, 0x6008, v9
	v_add_u32_e32 v92, 0x7008, v9
	v_add_u32_e32 v94, 0x8008, v9
	v_add_u32_e32 v96, 0x9008, v9
	v_add_u32_e32 v98, 0xa008, v9
	v_add_u32_e32 v100, 0xb008, v9
	v_add_u32_e32 v102, 0xc008, v9
	ds_read2_b32 v[72:73], v72 offset1:1
	ds_read2_b32 v[74:75], v74 offset1:1
	ds_read2_b32 v[76:77], v76 offset1:1
	ds_read2_b32 v[78:79], v78 offset1:1
	ds_read2_b32 v[80:81], v80 offset1:1
	ds_read2_b32 v[82:83], v82 offset1:1
	ds_read2_b32 v[84:85], v84 offset1:1
	ds_read2_b32 v[86:87], v86 offset1:1
	ds_read2_b32 v[88:89], v88 offset1:1
	ds_read2_b32 v[90:91], v90 offset1:1
	ds_read2_b32 v[92:93], v92 offset1:1
	ds_read2_b32 v[94:95], v94 offset1:1
	ds_read2_b32 v[96:97], v96 offset1:1
	ds_read2_b32 v[98:99], v98 offset1:1
	ds_read2_b32 v[100:101], v100 offset1:1
	ds_read2_b32 v[102:103], v102 offset1:1
	v_add_u32_e32 v104, 0xd008, v9
	v_add_u32_e32 v106, 0xe008, v9
	v_add_u32_e32 v108, 0xf008, v9
	v_add_u32_e32 v110, 0x10008, v9
	ds_read2_b32 v[104:105], v104 offset1:1
	ds_read2_b32 v[106:107], v106 offset1:1
	ds_read2_b32 v[108:109], v108 offset1:1
	ds_read2_b32 v[110:111], v110 offset1:1
	s_waitcnt lgkmcnt(14)
	v_mov_b32_e32 v112, v30
	v_mov_b32_e32 v113, v48
	v_mov_b32_e32 v114, v50
	v_mov_b32_e32 v115, v52
	v_mov_b32_e32 v52, v51
	v_mov_b32_e32 v50, v54
	v_mov_b32_e32 v51, v56
	v_mov_b32_e32 v56, v55
	v_mov_b32_e32 v54, v58
	v_mov_b32_e32 v55, v60
	v_mov_b32_e32 v60, v59
	v_mov_b32_e32 v58, v62
	v_mov_b32_e32 v59, v64
	v_mov_b32_e32 v64, v63
	v_mov_b32_e32 v62, v66
	v_mov_b32_e32 v63, v68
	v_mov_b32_e32 v68, v67
	v_mov_b32_e32 v66, v70
	v_mov_b32_e32 v67, v72
	v_mov_b32_e32 v72, v71
	v_mov_b32_e32 v70, v74
	v_mov_b32_e32 v71, v76
	v_mov_b32_e32 v48, v31
	v_mov_b32_e32 v76, v75
	v_mov_b32_e32 v30, v32
	v_mov_b32_e32 v31, v80
	v_mov_b32_e32 v80, v33
	v_mov_b32_e32 v32, v82
	s_waitcnt lgkmcnt(13)
	v_mov_b32_e32 v33, v84
	v_mov_b32_e32 v84, v83
	s_waitcnt lgkmcnt(12)
	v_mov_b32_e32 v74, v86
	s_waitcnt lgkmcnt(11)
	v_mov_b32_e32 v75, v88
	v_mov_b32_e32 v88, v87
	s_waitcnt lgkmcnt(10)
	v_mov_b32_e32 v82, v90
	s_waitcnt lgkmcnt(9)
	v_mov_b32_e32 v83, v92
	v_mov_b32_e32 v92, v91
	s_waitcnt lgkmcnt(8)
	v_mov_b32_e32 v86, v94
	s_waitcnt lgkmcnt(7)
	v_mov_b32_e32 v87, v96
	v_mov_b32_e32 v96, v95
	s_waitcnt lgkmcnt(6)
	v_mov_b32_e32 v90, v98
	s_waitcnt lgkmcnt(5)
	v_mov_b32_e32 v91, v100
	v_mov_b32_e32 v100, v99
	s_waitcnt lgkmcnt(4)
	v_mov_b32_e32 v94, v102
	s_waitcnt lgkmcnt(3)
	v_mov_b32_e32 v95, v104
	s_waitcnt lgkmcnt(2)
	v_mov_b32_e32 v98, v106
	v_pk_fma_f32 v[14:15], v[210:211], v[112:113], v[14:15] op_sel_hi:[0,1,1]
	v_pk_fma_f32 v[16:17], v[210:211], v[114:115], v[16:17] op_sel_hi:[0,1,1]
	v_pk_fma_f32 v[18:19], v[210:211], v[50:51], v[18:19] op_sel_hi:[0,1,1]
	v_pk_fma_f32 v[20:21], v[210:211], v[54:55], v[20:21] op_sel_hi:[0,1,1]
	v_pk_fma_f32 v[22:23], v[210:211], v[58:59], v[22:23] op_sel_hi:[0,1,1]
	v_pk_fma_f32 v[24:25], v[210:211], v[62:63], v[24:25] op_sel_hi:[0,1,1]
	v_pk_fma_f32 v[26:27], v[210:211], v[66:67], v[26:27] op_sel_hi:[0,1,1]
	v_pk_fma_f32 v[28:29], v[210:211], v[70:71], v[28:29] op_sel_hi:[0,1,1]
	v_fmac_f32_e32 v41, v210, v78
	s_waitcnt lgkmcnt(1)
	v_mov_b32_e32 v99, v108
	v_pk_fma_f32 v[14:15], v[212:213], v[48:49], v[14:15] op_sel_hi:[0,1,1]
	v_pk_fma_f32 v[16:17], v[212:213], v[52:53], v[16:17] op_sel_hi:[0,1,1]
	v_pk_fma_f32 v[18:19], v[212:213], v[56:57], v[18:19] op_sel_hi:[0,1,1]
	v_pk_fma_f32 v[20:21], v[212:213], v[60:61], v[20:21] op_sel_hi:[0,1,1]
	v_pk_fma_f32 v[22:23], v[212:213], v[64:65], v[22:23] op_sel_hi:[0,1,1]
	v_pk_fma_f32 v[24:25], v[212:213], v[68:69], v[24:25] op_sel_hi:[0,1,1]
	v_pk_fma_f32 v[26:27], v[212:213], v[72:73], v[26:27] op_sel_hi:[0,1,1]
	v_pk_fma_f32 v[28:29], v[212:213], v[76:77], v[28:29] op_sel_hi:[0,1,1]
	v_fmac_f32_e32 v41, v212, v79
	v_mov_b32_e32 v104, v103
	v_mov_b32_e32 v108, v107
	v_add_u32_e32 v9, 16, v9
	v_pk_fma_f32 v[14:15], v[214:215], v[30:31], v[14:15] op_sel_hi:[0,1,1]
	v_pk_fma_f32 v[16:17], v[214:215], v[32:33], v[16:17] op_sel_hi:[0,1,1]
	v_pk_fma_f32 v[18:19], v[214:215], v[74:75], v[18:19] op_sel_hi:[0,1,1]
	v_pk_fma_f32 v[20:21], v[214:215], v[82:83], v[20:21] op_sel_hi:[0,1,1]
	v_pk_fma_f32 v[22:23], v[214:215], v[86:87], v[22:23] op_sel_hi:[0,1,1]
	v_pk_fma_f32 v[24:25], v[214:215], v[90:91], v[24:25] op_sel_hi:[0,1,1]
	v_pk_fma_f32 v[26:27], v[214:215], v[94:95], v[26:27] op_sel_hi:[0,1,1]
	v_pk_fma_f32 v[28:29], v[214:215], v[98:99], v[28:29] op_sel_hi:[0,1,1]
	s_waitcnt lgkmcnt(0)
	v_fmac_f32_e32 v41, v214, v110
	v_pk_fma_f32 v[14:15], v[216:217], v[80:81], v[14:15] op_sel_hi:[0,1,1]
	v_pk_fma_f32 v[16:17], v[216:217], v[84:85], v[16:17] op_sel_hi:[0,1,1]
	v_pk_fma_f32 v[18:19], v[216:217], v[88:89], v[18:19] op_sel_hi:[0,1,1]
	v_pk_fma_f32 v[20:21], v[216:217], v[92:93], v[20:21] op_sel_hi:[0,1,1]
	v_pk_fma_f32 v[22:23], v[216:217], v[96:97], v[22:23] op_sel_hi:[0,1,1]
	v_pk_fma_f32 v[24:25], v[216:217], v[100:101], v[24:25] op_sel_hi:[0,1,1]
	v_pk_fma_f32 v[26:27], v[216:217], v[104:105], v[26:27] op_sel_hi:[0,1,1]
	v_pk_fma_f32 v[28:29], v[216:217], v[108:109], v[28:29] op_sel_hi:[0,1,1]
	v_fmac_f32_e32 v41, v216, v111
	v_add_u32_e32 v48, 0x1000, v9
	v_add_u32_e32 v50, 0x2000, v9
	v_add_u32_e32 v52, 0x3000, v9
	v_add_u32_e32 v54, 0x4000, v9
	v_add_u32_e32 v56, 0x5000, v9
	v_add_u32_e32 v58, 0x6000, v9
	v_add_u32_e32 v60, 0x7000, v9
	v_add_u32_e32 v62, 0x8000, v9
	v_add_u32_e32 v64, 0x9000, v9
	v_add_u32_e32 v66, 0xa000, v9
	v_add_u32_e32 v68, 0xb000, v9
	v_add_u32_e32 v70, 0xc000, v9
	ds_read2_b32 v[30:31], v9 offset1:1
	ds_read2_b32 v[32:33], v9 offset0:2 offset1:3
	v_add_u32_e32 v72, 0xd000, v9
	v_add_u32_e32 v74, 0xe000, v9
	v_add_u32_e32 v76, 0xf000, v9
	v_add_u32_e32 v78, 0x10000, v9
	ds_read2_b32 v[48:49], v48 offset1:1
	ds_read2_b32 v[50:51], v50 offset1:1
	ds_read2_b32 v[52:53], v52 offset1:1
	ds_read2_b32 v[54:55], v54 offset1:1
	ds_read2_b32 v[56:57], v56 offset1:1
	ds_read2_b32 v[58:59], v58 offset1:1
	ds_read2_b32 v[60:61], v60 offset1:1
	ds_read2_b32 v[62:63], v62 offset1:1
	ds_read2_b32 v[64:65], v64 offset1:1
	ds_read2_b32 v[66:67], v66 offset1:1
	ds_read2_b32 v[68:69], v68 offset1:1
	ds_read2_b32 v[70:71], v70 offset1:1
	v_add_u32_e32 v80, 0x1008, v9
	v_add_u32_e32 v82, 0x2008, v9
	v_add_u32_e32 v84, 0x3008, v9
	v_add_u32_e32 v86, 0x4008, v9
	v_add_u32_e32 v88, 0x5008, v9
	v_add_u32_e32 v90, 0x6008, v9
	v_add_u32_e32 v92, 0x7008, v9
	v_add_u32_e32 v94, 0x8008, v9
	v_add_u32_e32 v96, 0x9008, v9
	v_add_u32_e32 v98, 0xa008, v9
	v_add_u32_e32 v100, 0xb008, v9
	v_add_u32_e32 v102, 0xc008, v9
	ds_read2_b32 v[72:73], v72 offset1:1
	ds_read2_b32 v[74:75], v74 offset1:1
	ds_read2_b32 v[76:77], v76 offset1:1
	ds_read2_b32 v[78:79], v78 offset1:1
	ds_read2_b32 v[80:81], v80 offset1:1
	ds_read2_b32 v[82:83], v82 offset1:1
	ds_read2_b32 v[84:85], v84 offset1:1
	ds_read2_b32 v[86:87], v86 offset1:1
	ds_read2_b32 v[88:89], v88 offset1:1
	ds_read2_b32 v[90:91], v90 offset1:1
	ds_read2_b32 v[92:93], v92 offset1:1
	ds_read2_b32 v[94:95], v94 offset1:1
	ds_read2_b32 v[96:97], v96 offset1:1
	ds_read2_b32 v[98:99], v98 offset1:1
	ds_read2_b32 v[100:101], v100 offset1:1
	ds_read2_b32 v[102:103], v102 offset1:1
	v_add_u32_e32 v104, 0xd008, v9
	v_add_u32_e32 v106, 0xe008, v9
	v_add_u32_e32 v108, 0xf008, v9
	v_add_u32_e32 v110, 0x10008, v9
	ds_read2_b32 v[104:105], v104 offset1:1
	ds_read2_b32 v[106:107], v106 offset1:1
	ds_read2_b32 v[108:109], v108 offset1:1
	ds_read2_b32 v[110:111], v110 offset1:1
	s_waitcnt lgkmcnt(14)
	v_mov_b32_e32 v112, v30
	v_mov_b32_e32 v113, v48
	v_mov_b32_e32 v114, v50
	v_mov_b32_e32 v115, v52
	v_mov_b32_e32 v52, v51
	v_mov_b32_e32 v50, v54
	v_mov_b32_e32 v51, v56
	v_mov_b32_e32 v56, v55
	v_mov_b32_e32 v54, v58
	v_mov_b32_e32 v55, v60
	v_mov_b32_e32 v60, v59
	v_mov_b32_e32 v58, v62
	v_mov_b32_e32 v59, v64
	v_mov_b32_e32 v64, v63
	v_mov_b32_e32 v62, v66
	v_mov_b32_e32 v63, v68
	v_mov_b32_e32 v68, v67
	v_mov_b32_e32 v66, v70
	v_mov_b32_e32 v67, v72
	v_mov_b32_e32 v72, v71
	v_mov_b32_e32 v70, v74
	v_mov_b32_e32 v71, v76
	v_mov_b32_e32 v48, v31
	v_mov_b32_e32 v76, v75
	v_mov_b32_e32 v30, v32
	v_mov_b32_e32 v31, v80
	v_mov_b32_e32 v80, v33
	v_mov_b32_e32 v32, v82
	s_waitcnt lgkmcnt(13)
	v_mov_b32_e32 v33, v84
	v_mov_b32_e32 v84, v83
	s_waitcnt lgkmcnt(12)
	v_mov_b32_e32 v74, v86
	s_waitcnt lgkmcnt(11)
	v_mov_b32_e32 v75, v88
	v_mov_b32_e32 v88, v87
	s_waitcnt lgkmcnt(10)
	v_mov_b32_e32 v82, v90
	s_waitcnt lgkmcnt(9)
	v_mov_b32_e32 v83, v92
	v_mov_b32_e32 v92, v91
	s_waitcnt lgkmcnt(8)
	v_mov_b32_e32 v86, v94
	s_waitcnt lgkmcnt(7)
	v_mov_b32_e32 v87, v96
	v_mov_b32_e32 v96, v95
	s_waitcnt lgkmcnt(6)
	v_mov_b32_e32 v90, v98
	s_waitcnt lgkmcnt(5)
	v_mov_b32_e32 v91, v100
	v_mov_b32_e32 v100, v99
	s_waitcnt lgkmcnt(4)
	v_mov_b32_e32 v94, v102
	s_waitcnt lgkmcnt(3)
	v_mov_b32_e32 v95, v104
	s_waitcnt lgkmcnt(2)
	v_mov_b32_e32 v98, v106
	v_pk_fma_f32 v[14:15], v[218:219], v[112:113], v[14:15] op_sel_hi:[0,1,1]
	v_pk_fma_f32 v[16:17], v[218:219], v[114:115], v[16:17] op_sel_hi:[0,1,1]
	v_pk_fma_f32 v[18:19], v[218:219], v[50:51], v[18:19] op_sel_hi:[0,1,1]
	v_pk_fma_f32 v[20:21], v[218:219], v[54:55], v[20:21] op_sel_hi:[0,1,1]
	v_pk_fma_f32 v[22:23], v[218:219], v[58:59], v[22:23] op_sel_hi:[0,1,1]
	v_pk_fma_f32 v[24:25], v[218:219], v[62:63], v[24:25] op_sel_hi:[0,1,1]
	v_pk_fma_f32 v[26:27], v[218:219], v[66:67], v[26:27] op_sel_hi:[0,1,1]
	v_pk_fma_f32 v[28:29], v[218:219], v[70:71], v[28:29] op_sel_hi:[0,1,1]
	v_fmac_f32_e32 v41, v218, v78
	s_waitcnt lgkmcnt(1)
	v_mov_b32_e32 v99, v108
	v_pk_fma_f32 v[14:15], v[220:221], v[48:49], v[14:15] op_sel_hi:[0,1,1]
	v_pk_fma_f32 v[16:17], v[220:221], v[52:53], v[16:17] op_sel_hi:[0,1,1]
	v_pk_fma_f32 v[18:19], v[220:221], v[56:57], v[18:19] op_sel_hi:[0,1,1]
	v_pk_fma_f32 v[20:21], v[220:221], v[60:61], v[20:21] op_sel_hi:[0,1,1]
	v_pk_fma_f32 v[22:23], v[220:221], v[64:65], v[22:23] op_sel_hi:[0,1,1]
	v_pk_fma_f32 v[24:25], v[220:221], v[68:69], v[24:25] op_sel_hi:[0,1,1]
	v_pk_fma_f32 v[26:27], v[220:221], v[72:73], v[26:27] op_sel_hi:[0,1,1]
	v_pk_fma_f32 v[28:29], v[220:221], v[76:77], v[28:29] op_sel_hi:[0,1,1]
	v_fmac_f32_e32 v41, v220, v79
	v_mov_b32_e32 v104, v103
	v_mov_b32_e32 v108, v107
	v_add_u32_e32 v9, 16, v9
	v_pk_fma_f32 v[14:15], v[222:223], v[30:31], v[14:15] op_sel_hi:[0,1,1]
	v_pk_fma_f32 v[16:17], v[222:223], v[32:33], v[16:17] op_sel_hi:[0,1,1]
	v_pk_fma_f32 v[18:19], v[222:223], v[74:75], v[18:19] op_sel_hi:[0,1,1]
	v_pk_fma_f32 v[20:21], v[222:223], v[82:83], v[20:21] op_sel_hi:[0,1,1]
	v_pk_fma_f32 v[22:23], v[222:223], v[86:87], v[22:23] op_sel_hi:[0,1,1]
	v_pk_fma_f32 v[24:25], v[222:223], v[90:91], v[24:25] op_sel_hi:[0,1,1]
	v_pk_fma_f32 v[26:27], v[222:223], v[94:95], v[26:27] op_sel_hi:[0,1,1]
	v_pk_fma_f32 v[28:29], v[222:223], v[98:99], v[28:29] op_sel_hi:[0,1,1]
	s_waitcnt lgkmcnt(0)
	v_fmac_f32_e32 v41, v222, v110
	v_pk_fma_f32 v[14:15], v[224:225], v[80:81], v[14:15] op_sel_hi:[0,1,1]
	v_pk_fma_f32 v[16:17], v[224:225], v[84:85], v[16:17] op_sel_hi:[0,1,1]
	v_pk_fma_f32 v[18:19], v[224:225], v[88:89], v[18:19] op_sel_hi:[0,1,1]
	v_pk_fma_f32 v[20:21], v[224:225], v[92:93], v[20:21] op_sel_hi:[0,1,1]
	v_pk_fma_f32 v[22:23], v[224:225], v[96:97], v[22:23] op_sel_hi:[0,1,1]
	v_pk_fma_f32 v[24:25], v[224:225], v[100:101], v[24:25] op_sel_hi:[0,1,1]
	v_pk_fma_f32 v[26:27], v[224:225], v[104:105], v[26:27] op_sel_hi:[0,1,1]
	v_pk_fma_f32 v[28:29], v[224:225], v[108:109], v[28:29] op_sel_hi:[0,1,1]
	v_fmac_f32_e32 v41, v224, v111
	s_or_b64 exec, exec, s[14:15]
	ds_write2_b32 v39, v14, v15 offset1:16
	ds_write2_b32 v39, v16, v17 offset0:32 offset1:48
	ds_write2_b32 v39, v18, v19 offset0:64 offset1:80
	ds_write2_b32 v39, v20, v21 offset0:96 offset1:112
	ds_write2_b32 v39, v22, v23 offset0:128 offset1:144
	ds_write2_b32 v39, v24, v25 offset0:160 offset1:176
	ds_write2_b32 v39, v26, v27 offset0:192 offset1:208
	ds_write2_b32 v39, v28, v29 offset0:224 offset1:240
	ds_write_b32 v39, v41 offset:1024
	s_waitcnt lgkmcnt(0)
	s_barrier
	s_and_saveexec_b64 s[14:15], s[4:5]
	s_cbranch_execz .LBB0_8
	s_load_dwordx2 s[6:7], s[0:1], 0x28
	v_lshl_or_b32 v12, s26, 4, v34
	v_ashrrev_i32_e32 v13, 31, v12
	s_mov_b64 s[16:17], 0
	v_mov_b32_e32 v9, v4
	s_waitcnt lgkmcnt(0)
	v_lshl_add_u64 v[14:15], v[12:13], 2, s[6:7]
